# attention phase: K/V/Q flat_load -> global_load (no lgkmcnt coupling), 2nd-half vmcnt(0) drain only when no further loads are issued
# baseline (speedup 1.0000x reference)
; #define SLOAD8(i, t) do { sk[i] = *reinterpret_cast<const i32x4a*>(kg + (long)(t) * (64 * 512)); sv[i] = *reinterpret_cast<const i32x4a*>(vg + (long)(t) * VT_STRIDE); } while (0)
; __device__ __forceinline__ void attn_unit8(const bf16_t* __restrict__ Qb, const unsigned char* __restrict__ K8h, const unsigned char* __restrict__ VT8h, unsigned char* __restrict__ Ob, int seq, ATT_LAS char* lds, ...
;     ...
;   const int krow = tid >> 3, kch = tid & 7, kst = k8_off(krow, kch), vst = v8_off(tid >> 2, tid & 3);
;   const unsigned char* kg = K8h + (long)krow * 512 + kch * 16; const unsigned char* vg = VT8h + tid * 16;
;   i32x4a sk[2], sv[2];
;     ...
;   const int NT = seq / KVBLK;
;   SLOAD8(0, 0);
;   {
;     typedef float f32x4a __attribute__((ext_vector_type(4)));
;     const bf16_t* Qw = Qb + (long)(wid * QBLK + r32) * LDQ + hi * 8;
;     bf16x8 qr[8];
; #pragma unroll
;     for (int d0 = 0; d0 < 8; ++d0) qr[d0] = *reinterpret_cast<const bf16x8*>(Qw + d0 * 16);
;     float x[8][8]; float ss = 0.f;
; #pragma unroll
;     for (int d0 = 0; d0 < 8; ++d0)
; #pragma unroll
;       for (int e = 0; e < 8; ++e) { x[d0][e] = __uint_as_float((unsigned)(unsigned short)qr[d0][e] << 16); ss += x[d0][e] * x[d0][e]; }
;     { auto rr = __builtin_amdgcn_permlane32_swap(__float_as_uint(ss), __float_as_uint(ss), false, false); ss = __uint_as_float(rr[0]) + __uint_as_float(rr[1]); }
;     const float inv = 1.0f / sqrtf(ss * (1.0f / 128.0f) + 1e-6f);
; #pragma unroll
;     for (int d0 = 0; d0 < 8; ++d0) { const f32x4a g0 = *reinterpret_cast<const f32x4a*>(qg + d0 * 16 + hi * 8), g1 = *reinterpret_cast<const f32x4a*>(qg + d0 * 16 + hi * 8 + 4);
; #pragma unroll
;       for (int e = 0; e < 4; ++e) { x[d0][e] = x[d0][e] * inv * g0[e]; x[d0][4 + e] = x[d0][4 + e] * inv * g1[e]; } }
;     const int tq = tpos0 + wid * QBLK + r32;
; #pragma unroll
;     for (int ax = 0; ax < 2; ++ax) { const int pos = ax == 0 ? (tq >> 6) : (tq & 63);
; #pragma unroll
;       for (int h = 0; h < 2; ++h) { const f32x4a* tp = reinterpret_cast<const f32x4a*>(tab + (size_t)(pos * 32 + h * 16 + hi * 8) * 2);
; #pragma unroll
;         for (int e2 = 0; e2 < 4; ++e2) { const f32x4a cs = tp[e2];
.LBB0_548:
	s_lshl_b32 s27, s25, 8
	s_add_i32 s6, s27, s24
	s_ashr_i32 s7, s6, 31
	s_lshl_b64 s[22:23], s[6:7], 11
	s_lshl_b64 s[6:7], s[6:7], 12
	s_add_u32 s6, s4, s6
	v_mov_b32_e32 v209, v0
	s_addc_u32 s7, s5, s7
	s_lshl_b32 s82, s8, 7
	s_lshl_b32 s8, s8, 8
	s_add_u32 s52, s6, s8
	v_ashrrev_i32_e32 v204, 6, v209
	v_and_b32_e32 v203, 31, v209
	v_lshlrev_b32_e32 v132, 5, v204
	s_addc_u32 s53, s7, 0
	s_ashr_i32 s25, s24, 31
	v_or_b32_e32 v2, v132, v203
	s_lshl_b64 s[8:9], s[24:25], 9
	v_ashrrev_i32_e32 v3, 31, v2
	s_add_u32 s6, s19, s8
	v_bfe_u32 v205, v209, 5, 1
	v_lshlrev_b64 v[2:3], 12, v[2:3]
	s_addc_u32 s7, s28, s9
	s_lshl_b32 s25, s26, 7
	v_lshl_add_u64 v[2:3], s[52:53], 0, v[2:3]
	v_lshlrev_b32_e32 v134, 4, v205
	v_mov_b32_e32 v135, v131
	s_add_u32 s6, s6, s25
	v_lshl_add_u64 v[10:11], v[2:3], 0, v[134:135]
	v_and_b32_e32 v2, 32, v209
	v_mov_b32_e32 v3, v131
	s_addc_u32 s7, s7, 0
	s_ashr_i32 s24, s24, 4
	v_lshl_add_u64 v[12:13], s[12:13], 0, v[2:3]
	v_and_b32_e32 v2, 0x3fffffc0, v209
	v_ashrrev_i32_e32 v14, 3, v209
	s_and_b32 s24, s24, -4
	v_lshl_add_u32 v206, v2, 2, 0
	v_lshrrev_b32_e32 v2, 1, v14
	s_or_b32 s54, s26, s24
	v_xor_b32_e32 v2, v2, v209
	v_ashrrev_i32_e32 v17, 2, v209
	s_ashr_i32 s55, s54, 31
	v_lshlrev_b32_e32 v16, 4, v2
	v_lshrrev_b32_e32 v2, 2, v17
	v_ashrrev_i32_e32 v15, 31, v14
	s_lshl_b64 s[52:53], s[54:55], 13
	v_xor_b32_e32 v2, v2, v209
	v_lshlrev_b64 v[124:125], 9, v[14:15]
	v_lshlrev_b32_e32 v122, 4, v209
	s_add_u32 s52, s29, s52
	v_lshlrev_b32_e32 v18, 4, v2
	v_lshl_add_u64 v[2:3], s[6:7], 0, v[124:125]
	v_and_b32_e32 v130, 0x70, v122
	v_mov_b32_e32 v133, 0x7f7f7f7f
	s_addc_u32 s53, s30, s53
	v_lshl_add_u64 v[118:119], v[2:3], 0, v[130:131]
	v_ashrrev_i32_e32 v123, 31, v122
	global_load_dwordx4 v[178:181], v[10:11], off offset:128
	global_load_dwordx4 v[152:155], v[10:11], off offset:160
	global_load_dwordx4 v[182:185], v[10:11], off offset:192
	global_load_dwordx4 v[156:159], v[10:11], off offset:224
	global_load_dwordx4 v[160:163], v[12:13], off offset:448
	global_load_dwordx4 v[144:147], v[12:13], off offset:464
	global_load_dwordx4 v[54:57], v[12:13], off offset:320
	global_load_dwordx4 v[50:53], v[12:13], off offset:336
	v_lshl_add_u64 v[120:121], s[52:53], 0, v[122:123]
	global_load_dwordx4 v[6:9], v[118:119], off
	global_load_dwordx4 v[2:5], v[120:121], off
	global_load_dwordx4 v[186:189], v[12:13], off offset:384
	global_load_dwordx4 v[168:171], v[12:13], off offset:400
	global_load_dwordx4 v[86:89], v[12:13], off offset:256
	global_load_dwordx4 v[78:81], v[12:13], off offset:272
	global_load_dwordx4 v[110:113], v[10:11], off
	global_load_dwordx4 v[210:213], v[10:11], off offset:32
	global_load_dwordx4 v[114:117], v[10:11], off offset:64
	global_load_dwordx4 v[214:217], v[10:11], off offset:96
	global_load_dwordx4 v[102:105], v[12:13], off
	global_load_dwordx4 v[98:101], v[12:13], off offset:16
	global_load_dwordx4 v[94:97], v[12:13], off offset:64
	global_load_dwordx4 v[90:93], v[12:13], off offset:80
	global_load_dwordx4 v[106:109], v[12:13], off offset:128
	global_load_dwordx4 v[218:221], v[12:13], off offset:144
	global_load_dwordx4 v[222:225], v[12:13], off offset:192
	global_load_dwordx4 v[194:197], v[12:13], off offset:208
	v_lshlrev_b32_e32 v10, 7, v14
	v_and_or_b32 v208, v16, s31, v10
	v_or_b32_e32 v10, s27, v203
	v_add_u32_e32 v14, v10, v132
	v_lshlrev_b32_e32 v15, 3, v205
	v_ashrrev_i32_e32 v10, 1, v14
	v_lshlrev_b32_e32 v11, 6, v17
	v_and_or_b32 v10, v10, s33, v15
	v_and_or_b32 v207, v18, 48, v11
	v_ashrrev_i32_e32 v11, 31, v10
	v_lshl_add_u64 v[12:13], v[10:11], 3, s[14:15]
	global_load_dwordx4 v[82:85], v[12:13], off
	global_load_dwordx4 v[74:77], v[12:13], off offset:16
	global_load_dwordx4 v[70:73], v[12:13], off offset:32
	global_load_dwordx4 v[66:69], v[12:13], off offset:48
	v_or_b32_e32 v10, 16, v10
	v_ashrrev_i32_e32 v11, 31, v10
	v_lshl_add_u64 v[10:11], v[10:11], 3, s[14:15]
	global_load_dwordx4 v[62:65], v[10:11], off
	global_load_dwordx4 v[58:61], v[10:11], off offset:16
	global_load_dwordx4 v[46:49], v[10:11], off offset:32
	global_load_dwordx4 v[42:45], v[10:11], off offset:48
	v_lshlrev_b32_e32 v10, 5, v14
	v_and_or_b32 v10, v10, s34, v15
	v_lshlrev_b32_e32 v10, 3, v10
	v_mov_b32_e32 v11, v131
	v_lshl_add_u64 v[10:11], s[14:15], 0, v[10:11]
	global_load_dwordx4 v[38:41], v[10:11], off
	global_load_dwordx4 v[34:37], v[10:11], off offset:16
	global_load_dwordx4 v[30:33], v[10:11], off offset:32
	global_load_dwordx4 v[26:29], v[10:11], off offset:48
	global_load_dwordx4 v[22:25], v[10:11], off offset:128
	global_load_dwordx4 v[18:21], v[10:11], off offset:144
	global_load_dwordx4 v[14:17], v[10:11], off offset:160
	s_nop 0
	global_load_dwordx4 v[10:13], v[10:11], off offset:176
	s_waitcnt vmcnt(0)
	s_mov_b32 s84, 4
	v_and_b32_e32 v135, 63, v209
	s_mov_b32 s52, 0
	s_waitcnt vmcnt(0) lgkmcnt(0)
; __device__ __forceinline__ void attn_unit8(const bf16_t* __restrict__ Qb, const unsigned char* __restrict__ K8h, const unsigned char* __restrict__ VT8h, unsigned char* __restrict__ Ob, int seq, ATT_LAS char* lds, ...
;     ...
;     float x[8][8]; float ss = 0.f;
; #pragma unroll
;     for (int d0 = 0; d0 < 8; ++d0)
; #pragma unroll
;       for (int e = 0; e < 8; ++e) { x[d0][e] = __uint_as_float((unsigned)(unsigned short)qr[d0][e] << 16); ss += x[d0][e] * x[d0][e]; }
	v_lshlrev_b32_e32 v177, 16, v178
	v_lshlrev_b32_e32 v139, 16, v154
	v_mov_b32_e32 v136, v146
	v_lshlrev_b32_e32 v126, 16, v159
	v_lshlrev_b32_e32 v229, 16, v110
	v_mov_b32_e32 v137, v52
	v_and_b32_e32 v128, 0xffff0000, v159
	v_mov_b32_e32 v52, v147
	v_lshlrev_b32_e32 v138, 16, v158
	v_mov_b32_e32 v142, v144
	v_mov_b32_e32 v143, v50
	v_and_b32_e32 v141, 0xffff0000, v154
	v_and_b32_e32 v140, 0xffff0000, v158
	v_mov_b32_e32 v50, v145
	v_lshlrev_b32_e32 v145, 16, v153
	v_lshlrev_b32_e32 v144, 16, v157
	v_and_b32_e32 v147, 0xffff0000, v153
	v_and_b32_e32 v146, 0xffff0000, v157
	v_lshlrev_b32_e32 v151, 16, v152
	v_lshlrev_b32_e32 v150, 16, v156
	v_mov_b32_e32 v154, v160
	v_and_b32_e32 v153, 0xffff0000, v152
	v_and_b32_e32 v152, 0xffff0000, v156
	v_lshlrev_b32_e32 v157, 16, v181
	v_lshlrev_b32_e32 v156, 16, v185
	v_mov_b32_e32 v160, v170
	v_and_b32_e32 v159, 0xffff0000, v181
	v_and_b32_e32 v158, 0xffff0000, v185
	v_mov_b32_e32 v166, v168
	v_lshlrev_b32_e32 v168, 16, v183
	v_mov_b32_e32 v173, v88
	v_and_b32_e32 v170, 0xffff0000, v183
	v_mov_b32_e32 v88, v189
	v_mov_b32_e32 v181, v86
	v_mov_b32_e32 v86, v187
	v_lshlrev_b32_e32 v183, 16, v213
	v_mov_b32_e32 v187, v92
	v_and_b32_e32 v185, 0xffff0000, v213
	v_mov_b32_e32 v92, v197
	v_lshlrev_b32_e32 v189, 16, v212
	v_mov_b32_e32 v193, v90
	v_and_b32_e32 v191, 0xffff0000, v212
	v_mov_b32_e32 v90, v195
	v_lshlrev_b32_e32 v195, 16, v211
	v_mov_b32_e32 v198, v224
	v_and_b32_e32 v197, 0xffff0000, v211
	v_lshlrev_b32_e32 v213, 16, v210
	v_lshlrev_b32_e32 v212, 16, v214
	v_and_b32_e32 v211, 0xffff0000, v210
	v_and_b32_e32 v210, 0xffff0000, v214
	v_lshlrev_b32_e32 v214, 16, v117
	v_and_b32_e32 v224, 0xffff0000, v117
	v_mov_b32_e32 v227, v98
	v_mov_b32_e32 v98, v219
	v_lshlrev_b32_e32 v117, 16, v111
	v_and_b32_e32 v219, 0xffff0000, v111
	v_lshlrev_b32_e32 v228, 16, v114
	v_and_b32_e32 v111, 0xffff0000, v110
	v_and_b32_e32 v110, 0xffff0000, v114
	v_mul_f32_e32 v114, v229, v229
	v_fmac_f32_e32 v114, v111, v111
	v_fmac_f32_e32 v114, v117, v117
	v_lshlrev_b32_e32 v127, 16, v155
	v_and_b32_e32 v129, 0xffff0000, v155
	v_mov_b32_e32 v148, v162
	v_mov_b32_e32 v155, v54
	v_mov_b32_e32 v54, v161
	v_mov_b32_e32 v161, v80
	v_mov_b32_e32 v80, v171
	v_lshlrev_b32_e32 v162, 16, v184
	v_mov_b32_e32 v167, v78
	v_and_b32_e32 v164, 0xffff0000, v184
	v_mov_b32_e32 v78, v169
	v_lshlrev_b32_e32 v169, 16, v179
	v_and_b32_e32 v171, 0xffff0000, v179
	v_lshlrev_b32_e32 v176, 16, v182
	v_and_b32_e32 v179, 0xffff0000, v178
	v_and_b32_e32 v178, 0xffff0000, v182
	v_lshlrev_b32_e32 v182, 16, v217
	v_and_b32_e32 v184, 0xffff0000, v217
	v_mov_b32_e32 v217, v94
	v_mov_b32_e32 v94, v223
	v_mov_b32_e32 v223, v100
	v_mov_b32_e32 v100, v221
	v_lshlrev_b32_e32 v221, 16, v112
	v_fmac_f32_e32 v114, v219, v219
	v_mov_b32_e32 v149, v56
	v_mov_b32_e32 v56, v163
	v_lshlrev_b32_e32 v163, 16, v180
	v_and_b32_e32 v165, 0xffff0000, v180
	v_mov_b32_e32 v180, v186
	v_mov_b32_e32 v186, v196
	v_mov_b32_e32 v192, v194
	v_lshlrev_b32_e32 v194, 16, v215
	v_mov_b32_e32 v199, v96
	v_and_b32_e32 v196, 0xffff0000, v215
	v_mov_b32_e32 v96, v225
	v_lshlrev_b32_e32 v215, 16, v113
	v_and_b32_e32 v225, 0xffff0000, v113
	v_and_b32_e32 v113, 0xffff0000, v112
	v_fmac_f32_e32 v114, v221, v221
	v_fmac_f32_e32 v114, v113, v113
	v_fmac_f32_e32 v114, v215, v215
	v_fmac_f32_e32 v114, v225, v225
	v_fmac_f32_e32 v114, v213, v213
	v_fmac_f32_e32 v114, v211, v211
	v_fmac_f32_e32 v114, v195, v195
	v_fmac_f32_e32 v114, v197, v197
	v_fmac_f32_e32 v114, v189, v189
	v_fmac_f32_e32 v114, v191, v191
	v_fmac_f32_e32 v114, v183, v183
	v_fmac_f32_e32 v114, v185, v185
	v_mov_b32_e32 v172, v188
	v_lshlrev_b32_e32 v188, 16, v216
	v_and_b32_e32 v190, 0xffff0000, v216
	v_mov_b32_e32 v216, v222
	v_mov_b32_e32 v222, v220
	v_lshlrev_b32_e32 v220, 16, v116
	v_mov_b32_e32 v226, v218
	v_and_b32_e32 v112, 0xffff0000, v116
	v_lshlrev_b32_e32 v116, 16, v115
	v_and_b32_e32 v218, 0xffff0000, v115
	v_pk_fma_f32 v[114:115], v[228:229], v[228:229], v[114:115] op_sel_hi:[1,1,0]
	v_mul_f32_e32 v230, v177, v177
	v_pk_fma_f32 v[114:115], v[110:111], v[110:111], v[114:115]
	v_mov_b32_e32 v174, v128
	v_pk_fma_f32 v[114:115], v[116:117], v[116:117], v[114:115]
	v_mov_b32_e32 v175, v126
	v_pk_fma_f32 v[114:115], v[218:219], v[218:219], v[114:115]
	s_nop 0
	v_pk_fma_f32 v[114:115], v[220:221], v[220:221], v[114:115]
	s_nop 0
	v_pk_fma_f32 v[114:115], v[112:113], v[112:113], v[114:115]
	s_nop 0
	v_pk_fma_f32 v[114:115], v[214:215], v[214:215], v[114:115]
	s_nop 0
	v_pk_fma_f32 v[114:115], v[224:225], v[224:225], v[114:115]
	s_nop 0
	v_pk_fma_f32 v[114:115], v[212:213], v[212:213], v[114:115]
	s_nop 0
	v_pk_fma_f32 v[114:115], v[210:211], v[210:211], v[114:115]
	s_nop 0
	v_pk_fma_f32 v[114:115], v[194:195], v[194:195], v[114:115]
	s_nop 0
	v_pk_fma_f32 v[114:115], v[196:197], v[196:197], v[114:115]
	s_nop 0
	v_pk_fma_f32 v[114:115], v[188:189], v[188:189], v[114:115]
	s_nop 0
	v_pk_fma_f32 v[114:115], v[190:191], v[190:191], v[114:115]
	s_nop 0
	v_pk_fma_f32 v[114:115], v[182:183], v[182:183], v[114:115]
	s_nop 0
	v_pk_fma_f32 v[114:115], v[184:185], v[184:185], v[114:115]
	s_nop 0
	v_pk_add_f32 v[114:115], v[230:231], v[114:115] op_sel_hi:[0,1]
	v_mul_f32_e32 v230, v179, v179
	v_pk_add_f32 v[114:115], v[230:231], v[114:115] op_sel_hi:[0,1]
	v_mul_f32_e32 v230, v169, v169
	v_pk_add_f32 v[114:115], v[230:231], v[114:115] op_sel_hi:[0,1]
	v_mul_f32_e32 v230, v171, v171
	v_pk_add_f32 v[114:115], v[230:231], v[114:115] op_sel_hi:[0,1]
	v_mul_f32_e32 v230, v163, v163
	v_pk_add_f32 v[114:115], v[230:231], v[114:115] op_sel_hi:[0,1]
	v_mul_f32_e32 v230, v165, v165
	v_pk_add_f32 v[114:115], v[230:231], v[114:115] op_sel_hi:[0,1]
; __device__ __forceinline__ void attn_unit8(const bf16_t* __restrict__ Qb, const unsigned char* __restrict__ K8h, const unsigned char* __restrict__ VT8h, unsigned char* __restrict__ Ob, int seq, ATT_LAS char* lds, ...
;     ...
;     { auto rr = __builtin_amdgcn_permlane32_swap(__float_as_uint(ss), __float_as_uint(ss), false, false); ss = __uint_as_float(rr[0]) + __uint_as_float(rr[1]); }
;     const float inv = 1.0f / sqrtf(ss * (1.0f / 128.0f) + 1e-6f);
; #pragma unroll
;     for (int d0 = 0; d0 < 8; ++d0) { const f32x4a g0 = *reinterpret_cast<const f32x4a*>(qg + d0 * 16 + hi * 8), g1 = *reinterpret_cast<const f32x4a*>(qg + d0 * 16 + hi * 8 + 4);
; #pragma unroll
;       for (int e = 0; e < 4; ++e) { x[d0][e] = x[d0][e] * inv * g0[e]; x[d0][4 + e] = x[d0][4 + e] * inv * g1[e]; } }
	v_mul_f32_e32 v230, v157, v157
	v_pk_add_f32 v[114:115], v[230:231], v[114:115] op_sel_hi:[0,1]
	v_mul_f32_e32 v230, v159, v159
	v_pk_add_f32 v[114:115], v[230:231], v[114:115] op_sel_hi:[0,1]
	v_mul_f32_e32 v230, v151, v151
	v_pk_add_f32 v[114:115], v[230:231], v[114:115] op_sel_hi:[0,1]
	v_mul_f32_e32 v230, v153, v153
	v_pk_add_f32 v[114:115], v[230:231], v[114:115] op_sel_hi:[0,1]
	v_mul_f32_e32 v230, v145, v145
	v_pk_add_f32 v[114:115], v[230:231], v[114:115] op_sel_hi:[0,1]
	v_mul_f32_e32 v230, v147, v147
	v_pk_add_f32 v[114:115], v[230:231], v[114:115] op_sel_hi:[0,1]
	v_mul_f32_e32 v230, v139, v139
	v_pk_add_f32 v[114:115], v[230:231], v[114:115] op_sel_hi:[0,1]
	v_mul_f32_e32 v230, v141, v141
	v_pk_add_f32 v[114:115], v[230:231], v[114:115] op_sel_hi:[0,1]
	v_mul_f32_e32 v230, v127, v127
	v_pk_add_f32 v[114:115], v[230:231], v[114:115] op_sel_hi:[0,1]
	v_mul_f32_e32 v230, v129, v129
	v_pk_add_f32 v[114:115], v[230:231], v[114:115] op_sel_hi:[0,1]
	v_pk_fma_f32 v[114:115], v[176:177], v[176:177], v[114:115]
	v_mul_f32_e32 v230, v126, v126
	v_pk_fma_f32 v[114:115], v[178:179], v[178:179], v[114:115]
	s_nop 0
	v_pk_fma_f32 v[114:115], v[168:169], v[168:169], v[114:115]
	s_nop 0
	v_pk_fma_f32 v[114:115], v[170:171], v[170:171], v[114:115]
	s_nop 0
	v_pk_fma_f32 v[114:115], v[162:163], v[162:163], v[114:115]
	s_nop 0
	v_pk_fma_f32 v[114:115], v[164:165], v[164:165], v[114:115]
	s_nop 0
	v_pk_fma_f32 v[114:115], v[156:157], v[156:157], v[114:115]
	s_nop 0
	v_pk_fma_f32 v[114:115], v[158:159], v[158:159], v[114:115]
	s_nop 0
	v_pk_fma_f32 v[114:115], v[150:151], v[150:151], v[114:115]
	s_nop 0
	v_pk_fma_f32 v[114:115], v[152:153], v[152:153], v[114:115]
	s_nop 0
	v_pk_fma_f32 v[114:115], v[144:145], v[144:145], v[114:115]
	s_nop 0
	v_pk_fma_f32 v[114:115], v[146:147], v[146:147], v[114:115]
	s_nop 0
	v_pk_fma_f32 v[114:115], v[138:139], v[138:139], v[114:115]
	s_nop 0
	v_pk_fma_f32 v[114:115], v[140:141], v[140:141], v[114:115]
	s_nop 0
	v_pk_add_f32 v[114:115], v[230:231], v[114:115] op_sel_hi:[0,1]
	v_pk_fma_f32 v[114:115], v[174:175], v[174:175], v[114:115]
	s_nop 0
	v_mov_b32_e32 v115, v114
	s_nop 1
	v_permlane32_swap_b32_e32 v114, v115
	v_add_f32_e32 v114, v114, v115
	v_fmamk_f32 v114, v114, 0x3c000000, v200
	v_mul_f32_e32 v115, 0x4f800000, v114
	v_cmp_gt_f32_e32 vcc, s35, v114
	s_nop 1
	v_cndmask_b32_e32 v174, v114, v115, vcc
	v_sqrt_f32_e32 v175, v174
	v_mov_b32_e32 v114, v108
	v_mov_b32_e32 v115, v104
	v_mov_b32_e32 v104, v109
	v_add_u32_e32 v108, -1, v175
	v_fma_f32 v109, -v108, v175, v174
	v_cmp_ge_f32_e64 s[6:7], 0, v109
	v_add_u32_e32 v109, 1, v175
	s_nop 0
	v_cndmask_b32_e64 v108, v175, v108, s[6:7]
	v_fma_f32 v175, -v109, v175, v174
	v_cmp_lt_f32_e64 s[6:7], 0, v175
	s_nop 1
	v_cndmask_b32_e64 v108, v108, v109, s[6:7]
	v_mul_f32_e32 v109, 0x37800000, v108
	v_cndmask_b32_e32 v108, v108, v109, vcc
	v_cmp_class_f32_e32 vcc, v174, v201
	v_mov_b32_e32 v109, v102
	s_nop 0
	v_cndmask_b32_e32 v174, v108, v174, vcc
	v_div_scale_f32 v175, s[6:7], v174, v174, 1.0
	v_rcp_f32_e32 v230, v175
	v_mov_b32_e32 v108, v106
	v_fma_f32 v102, -v175, v230, 1.0
	v_fmac_f32_e32 v230, v102, v230
	v_div_scale_f32 v102, vcc, 1.0, v174, 1.0
	v_mul_f32_e32 v106, v102, v230
	v_fma_f32 v231, -v175, v106, v102
	v_fmac_f32_e32 v106, v231, v230
	v_fma_f32 v102, -v175, v106, v102
	v_div_fmas_f32 v102, v102, v230, v106
	v_div_fixup_f32 v106, v102, v174, 1.0
	v_pk_mul_f32 v[110:111], v[106:107], v[110:111] op_sel_hi:[0,1]
	v_mov_b32_e32 v102, v107
	v_pk_mul_f32 v[102:103], v[102:103], v[110:111]
	v_pk_mul_f32 v[110:111], v[106:107], v[112:113] op_sel_hi:[0,1]
	v_pk_mul_f32 v[98:99], v[98:99], v[110:111]
	v_pk_mul_f32 v[110:111], v[106:107], v[116:117] op_sel_hi:[0,1]
	v_pk_mul_f32 v[110:111], v[114:115], v[110:111]
	v_pk_mul_f32 v[114:115], v[106:107], v[218:219] op_sel_hi:[0,1]
	v_pk_mul_f32 v[116:117], v[106:107], v[188:189] op_sel_hi:[0,1]
	v_pk_mul_f32 v[188:189], v[106:107], v[210:211] op_sel_hi:[0,1]
	v_pk_mul_f32 v[174:175], v[106:107], v[228:229] op_sel_hi:[0,1]
	v_pk_mul_f32 v[104:105], v[104:105], v[114:115]
	v_pk_mul_f32 v[114:115], v[106:107], v[224:225] op_sel_hi:[0,1]
	v_pk_mul_f32 v[94:95], v[94:95], v[188:189]
	v_pk_mul_f32 v[188:189], v[106:107], v[190:191] op_sel_hi:[0,1]
	v_pk_mul_f32 v[182:183], v[106:107], v[182:183] op_sel_hi:[0,1]
	v_pk_mul_f32 v[162:163], v[106:107], v[162:163] op_sel_hi:[0,1]
	v_pk_mul_f32 v[164:165], v[106:107], v[164:165] op_sel_hi:[0,1]
	v_pk_mul_f32 v[156:157], v[106:107], v[156:157] op_sel_hi:[0,1]
	v_pk_mul_f32 v[138:139], v[106:107], v[138:139] op_sel_hi:[0,1]
	v_pk_mul_f32 v[140:141], v[106:107], v[140:141] op_sel_hi:[0,1]
	v_pk_mul_f32 v[126:127], v[106:107], v[126:127] op_sel_hi:[0,1]
	v_pk_mul_f32 v[108:109], v[108:109], v[174:175]
	v_pk_mul_f32 v[174:175], v[106:107], v[220:221] op_sel_hi:[0,1]
	v_pk_mul_f32 v[112:113], v[106:107], v[214:215] op_sel_hi:[0,1]
	v_pk_mul_f32 v[100:101], v[100:101], v[114:115]
	v_pk_mul_f32 v[114:115], v[106:107], v[212:213] op_sel_hi:[0,1]
	v_pk_mul_f32 v[90:91], v[90:91], v[188:189]
	v_pk_mul_f32 v[188:189], v[106:107], v[194:195] op_sel_hi:[0,1]
	v_pk_mul_f32 v[182:183], v[186:187], v[182:183]
	v_pk_mul_f32 v[186:187], v[106:107], v[196:197] op_sel_hi:[0,1]
	v_pk_mul_f32 v[184:185], v[106:107], v[184:185] op_sel_hi:[0,1]
	v_pk_mul_f32 v[176:177], v[106:107], v[176:177] op_sel_hi:[0,1]
	v_pk_mul_f32 v[162:163], v[162:163], v[166:167]
	v_pk_mul_f32 v[166:167], v[106:107], v[178:179] op_sel_hi:[0,1]
	v_pk_mul_f32 v[78:79], v[164:165], v[78:79]
	v_pk_mul_f32 v[164:165], v[106:107], v[168:169] op_sel_hi:[0,1]
	v_pk_mul_f32 v[156:157], v[156:157], v[160:161]
; __device__ __forceinline__ void attn_unit8(const bf16_t* __restrict__ Qb, const unsigned char* __restrict__ K8h, const unsigned char* __restrict__ VT8h, unsigned char* __restrict__ Ob, int seq, ATT_LAS char* lds, ...
;     ...
;     const float inv = 1.0f / sqrtf(ss * (1.0f / 128.0f) + 1e-6f);
; #pragma unroll
;     for (int d0 = 0; d0 < 8; ++d0) { const f32x4a g0 = *reinterpret_cast<const f32x4a*>(qg + d0 * 16 + hi * 8), g1 = *reinterpret_cast<const f32x4a*>(qg + d0 * 16 + hi * 8 + 4);
; #pragma unroll
;       for (int e = 0; e < 4; ++e) { x[d0][e] = x[d0][e] * inv * g0[e]; x[d0][4 + e] = x[d0][4 + e] * inv * g1[e]; } }
;     const int tq = tpos0 + wid * QBLK + r32;
; #pragma unroll
;     for (int ax = 0; ax < 2; ++ax) { const int pos = ax == 0 ? (tq >> 6) : (tq & 63);
; #pragma unroll
;       for (int h = 0; h < 2; ++h) { const f32x4a* tp = reinterpret_cast<const f32x4a*>(tab + (size_t)(pos * 32 + h * 16 + hi * 8) * 2);
; #pragma unroll
;         for (int e2 = 0; e2 < 4; ++e2) { const f32x4a cs = tp[e2];
; #pragma unroll
;           for (int k = 0; k < 2; ++k) { const int e = 2 * e2 + k; const float c = cs[2 * k], s = cs[2 * k + 1]; const float u0 = x[ax * 4 + h][e], u1 = x[ax * 4 + 2 + h][e];
;             x[ax * 4 + h][e] = u0 * c - u1 * s; x[ax * 4 + 2 + h][e] = u1 * c + u0 * s; } } } }
	v_pk_mul_f32 v[160:161], v[106:107], v[170:171] op_sel_hi:[0,1]
	v_pk_mul_f32 v[158:159], v[106:107], v[158:159] op_sel_hi:[0,1]
	v_pk_mul_f32 v[150:151], v[106:107], v[150:151] op_sel_hi:[0,1]
	v_pk_mul_f32 v[138:139], v[138:139], v[142:143]
	v_pk_mul_f32 v[142:143], v[106:107], v[152:153] op_sel_hi:[0,1]
	v_pk_mul_f32 v[50:51], v[140:141], v[50:51]
	v_pk_mul_f32 v[140:141], v[106:107], v[144:145] op_sel_hi:[0,1]
	v_pk_mul_f32 v[126:127], v[126:127], v[136:137]
	v_pk_mul_f32 v[136:137], v[106:107], v[146:147] op_sel_hi:[0,1]
	v_pk_mul_f32 v[106:107], v[106:107], v[128:129] op_sel_hi:[0,1]
	v_pk_mul_f32 v[52:53], v[106:107], v[52:53]
	v_pk_mul_f32 v[106:107], v[108:109], v[82:83] op_sel:[1,0] op_sel_hi:[0,1]
	v_pk_mul_f32 v[82:83], v[108:109], v[82:83]
	v_sub_f32_e32 v106, v106, v107
	v_add_f32_e32 v107, v83, v82
	v_pk_mul_f32 v[82:83], v[102:103], v[84:85] op_sel:[1,0] op_sel_hi:[0,1]
	v_sub_f32_e32 v108, v82, v83
	v_pk_mul_f32 v[82:83], v[102:103], v[84:85]
	v_pk_mul_f32 v[174:175], v[226:227], v[174:175]
	v_add_f32_e32 v84, v83, v82
	v_pk_mul_f32 v[82:83], v[110:111], v[74:75] op_sel:[1,0] op_sel_hi:[0,1]
	v_pk_mul_f32 v[74:75], v[110:111], v[74:75]
	v_sub_f32_e32 v82, v82, v83
	v_add_f32_e32 v83, v75, v74
	v_pk_mul_f32 v[74:75], v[104:105], v[76:77] op_sel:[1,0] op_sel_hi:[0,1]
	v_sub_f32_e32 v85, v74, v75
	v_pk_mul_f32 v[74:75], v[104:105], v[76:77]
	v_pk_mul_f32 v[112:113], v[222:223], v[112:113]
	v_add_f32_e32 v76, v75, v74
	v_pk_mul_f32 v[74:75], v[174:175], v[70:71] op_sel:[1,0] op_sel_hi:[0,1]
	v_pk_mul_f32 v[70:71], v[174:175], v[70:71]
	v_sub_f32_e32 v74, v74, v75
	v_add_f32_e32 v75, v71, v70
	v_pk_mul_f32 v[70:71], v[98:99], v[72:73] op_sel:[1,0] op_sel_hi:[0,1]
	v_sub_f32_e32 v77, v70, v71
	v_pk_mul_f32 v[70:71], v[98:99], v[72:73]
	v_pk_mul_f32 v[114:115], v[216:217], v[114:115]
	v_add_f32_e32 v72, v71, v70
	v_pk_mul_f32 v[70:71], v[112:113], v[66:67] op_sel:[1,0] op_sel_hi:[0,1]
	v_pk_mul_f32 v[66:67], v[112:113], v[66:67]
	v_sub_f32_e32 v70, v70, v71
	v_add_f32_e32 v71, v67, v66
	v_pk_mul_f32 v[66:67], v[100:101], v[68:69] op_sel:[1,0] op_sel_hi:[0,1]
	v_sub_f32_e32 v73, v66, v67
	v_pk_mul_f32 v[66:67], v[100:101], v[68:69]
	v_pk_mul_f32 v[188:189], v[198:199], v[188:189]
	v_add_f32_e32 v68, v67, v66
	v_pk_mul_f32 v[66:67], v[114:115], v[62:63] op_sel:[1,0] op_sel_hi:[0,1]
	v_pk_mul_f32 v[62:63], v[114:115], v[62:63]
	v_sub_f32_e32 v66, v66, v67
	v_add_f32_e32 v67, v63, v62
	v_pk_mul_f32 v[62:63], v[94:95], v[64:65] op_sel:[1,0] op_sel_hi:[0,1]
	v_sub_f32_e32 v69, v62, v63
	v_pk_mul_f32 v[62:63], v[94:95], v[64:65]
	v_pk_mul_f32 v[96:97], v[96:97], v[186:187]
	v_add_f32_e32 v64, v63, v62
	v_pk_mul_f32 v[62:63], v[188:189], v[58:59] op_sel:[1,0] op_sel_hi:[0,1]
	v_pk_mul_f32 v[58:59], v[188:189], v[58:59]
	v_sub_f32_e32 v62, v62, v63
	v_add_f32_e32 v63, v59, v58
	v_pk_mul_f32 v[58:59], v[96:97], v[60:61] op_sel:[1,0] op_sel_hi:[0,1]
	v_pk_mul_f32 v[116:117], v[192:193], v[116:117]
	v_sub_f32_e32 v65, v58, v59
	v_pk_mul_f32 v[58:59], v[96:97], v[60:61]
	v_pk_mul_f32 v[92:93], v[92:93], v[184:185]
	v_add_f32_e32 v60, v59, v58
	v_pk_mul_f32 v[58:59], v[116:117], v[46:47] op_sel:[1,0] op_sel_hi:[0,1]
	v_pk_mul_f32 v[46:47], v[116:117], v[46:47]
	v_sub_f32_e32 v58, v58, v59
	v_add_f32_e32 v59, v47, v46
	v_pk_mul_f32 v[46:47], v[90:91], v[48:49] op_sel:[1,0] op_sel_hi:[0,1]
	v_sub_f32_e32 v61, v46, v47
	v_pk_mul_f32 v[46:47], v[90:91], v[48:49]
	v_pk_mul_f32 v[176:177], v[176:177], v[180:181]
	v_add_f32_e32 v48, v47, v46
	v_pk_mul_f32 v[46:47], v[182:183], v[42:43] op_sel:[1,0] op_sel_hi:[0,1]
	v_pk_mul_f32 v[42:43], v[182:183], v[42:43]
	v_sub_f32_e32 v46, v46, v47
	v_add_f32_e32 v47, v43, v42
	v_pk_mul_f32 v[42:43], v[92:93], v[44:45] op_sel:[1,0] op_sel_hi:[0,1]
	v_sub_f32_e32 v49, v42, v43
	v_pk_mul_f32 v[42:43], v[92:93], v[44:45]
	v_pk_mul_f32 v[86:87], v[166:167], v[86:87]
	v_add_f32_e32 v44, v43, v42
	v_pk_mul_f32 v[42:43], v[176:177], v[38:39] op_sel:[1,0] op_sel_hi:[0,1]
	v_pk_mul_f32 v[38:39], v[176:177], v[38:39]
	v_sub_f32_e32 v42, v42, v43
	v_add_f32_e32 v43, v39, v38
	v_pk_mul_f32 v[38:39], v[86:87], v[40:41] op_sel:[1,0] op_sel_hi:[0,1]
	v_pk_mul_f32 v[164:165], v[164:165], v[172:173]
	v_sub_f32_e32 v45, v38, v39
	v_pk_mul_f32 v[38:39], v[86:87], v[40:41]
	v_pk_mul_f32 v[88:89], v[160:161], v[88:89]
	v_add_f32_e32 v40, v39, v38
	v_pk_mul_f32 v[38:39], v[164:165], v[34:35] op_sel:[1,0] op_sel_hi:[0,1]
	v_pk_mul_f32 v[34:35], v[164:165], v[34:35]
	v_sub_f32_e32 v38, v38, v39
	v_add_f32_e32 v39, v35, v34
	v_pk_mul_f32 v[34:35], v[88:89], v[36:37] op_sel:[1,0] op_sel_hi:[0,1]
	v_sub_f32_e32 v41, v34, v35
	v_pk_mul_f32 v[34:35], v[88:89], v[36:37]
	v_pk_mul_f32 v[80:81], v[158:159], v[80:81]
	v_add_f32_e32 v36, v35, v34
	v_pk_mul_f32 v[34:35], v[162:163], v[30:31] op_sel:[1,0] op_sel_hi:[0,1]
	v_pk_mul_f32 v[30:31], v[162:163], v[30:31]
	v_sub_f32_e32 v34, v34, v35
	v_add_f32_e32 v35, v31, v30
	v_pk_mul_f32 v[30:31], v[78:79], v[32:33] op_sel:[1,0] op_sel_hi:[0,1]
	v_sub_f32_e32 v37, v30, v31
	v_pk_mul_f32 v[30:31], v[78:79], v[32:33]
	v_pk_mul_f32 v[150:151], v[150:151], v[154:155]
	v_add_f32_e32 v32, v31, v30
	v_pk_mul_f32 v[30:31], v[156:157], v[26:27] op_sel:[1,0] op_sel_hi:[0,1]
	v_pk_mul_f32 v[26:27], v[156:157], v[26:27]
	v_sub_f32_e32 v30, v30, v31
	v_add_f32_e32 v31, v27, v26
	v_pk_mul_f32 v[26:27], v[80:81], v[28:29] op_sel:[1,0] op_sel_hi:[0,1]
	v_sub_f32_e32 v33, v26, v27
	v_pk_mul_f32 v[26:27], v[80:81], v[28:29]
	v_pk_mul_f32 v[54:55], v[142:143], v[54:55]
	v_add_f32_e32 v28, v27, v26
	v_pk_mul_f32 v[26:27], v[150:151], v[22:23] op_sel:[1,0] op_sel_hi:[0,1]
	v_pk_mul_f32 v[22:23], v[150:151], v[22:23]
; #define ATT_LAS __attribute__((address_space(3)))
; template <bool WAITSTATES>
; __device__ __forceinline__ void qkt8(f32x16& p0, f32x16& p1, const ATT_LAS char* Ks, const i32x8a (&q8)[2], int r32, int hi, int one) {
;   p0 = f32x16{}; p1 = f32x16{};
;   const i32x8a k00 = ld32(Ks + k8_off(r32, 2 * hi), Ks + k8_off(r32, 2 * hi + 1)), k10 = ld32(Ks + k8_off(32 + r32, 2 * hi), Ks + k8_off(32 + r32, 2 * hi + 1));
;   const i32x8a k01 = ld32(Ks + k8_off(r32, 4 + 2 * hi), Ks + k8_off(r32, 5 + 2 * hi)), k11 = ld32(Ks + k8_off(32 + r32, 4 + 2 * hi), Ks + k8_off(32 + r32, 5 + 2 * hi));
;   asm volatile("s_nop 1" ::: "memory");
;   __builtin_amdgcn_s_setprio(1); MFMA8(p0, k00, q8[0], one); MFMA8(p1, k10, q8[0], one); MFMA8(p0, k01, q8[1], one); MFMA8(p1, k11, q8[1], one); __builtin_amdgcn_s_setprio(0);
; __device__ __forceinline__ void attn_unit8(const bf16_t* __restrict__ Qb, const unsigned char* __restrict__ K8h, const unsigned char* __restrict__ VT8h, unsigned char* __restrict__ Ob, int seq, ATT_LAS char* lds, ...
;     ...
;           for (int k = 0; k < 2; ++k) { const int e = 2 * e2 + k; const float c = cs[2 * k], s = cs[2 * k + 1]; const float u0 = x[ax * 4 + h][e], u1 = x[ax * 4 + 2 + h][e];
;             x[ax * 4 + h][e] = u0 * c - u1 * s; x[ax * 4 + 2 + h][e] = u1 * c + u0 * s; } } } }
; #pragma unroll
;     for (int s = 0; s < 2; ++s)
;       q8[s] = (i32x8a){(int)pk4f8(x[4 * s][0], x[4 * s][1], x[4 * s][2], x[4 * s][3]), (int)pk4f8(x[4 * s][4], x[4 * s][5], x[4 * s][6], x[4 * s][7]),
;                        (int)pk4f8(x[4 * s + 1][0], x[4 * s + 1][1], x[4 * s + 1][2], x[4 * s + 1][3]), (int)pk4f8(x[4 * s + 1][4], x[4 * s + 1][5], x[4 * s + 1][6], x[4 * s + 1][7]),
;                        (int)pk4f8(x[4 * s + 2][0], x[4 * s + 2][1], x[4 * s + 2][2], x[4 * s + 2][3]), (int)pk4f8(x[4 * s + 2][4], x[4 * s + 2][5], x[4 * s + 2][6], x[4 * s + 2][7]),
;                        (int)pk4f8(x[4 * s + 3][0], x[4 * s + 3][1], x[4 * s + 3][2], x[4 * s + 3][3]), (int)pk4f8(x[4 * s + 3][4], x[4 * s + 3][5], x[4 * s + 3][6], x[4 * s + 3][7])};
;   }
;   f32x16 pA0, pA1, pB0, pB1; float mnA, mnB, alA, alB; i32x8a pa;
;   asm volatile("s_waitcnt vmcnt(0)" ::: "memory"); SWRITE8(0, 0); __syncthreads();
;   qkt8<true>(pA0, pA1, K_lds, q8, r32, hi, one); partialSM8(pA0, pA1, m_reg, mnA, alA);
	v_sub_f32_e32 v26, v26, v27
	v_add_f32_e32 v27, v23, v22
	v_pk_mul_f32 v[22:23], v[54:55], v[24:25] op_sel:[1,0] op_sel_hi:[0,1]
	v_pk_mul_f32 v[140:141], v[140:141], v[148:149]
	v_sub_f32_e32 v29, v22, v23
	v_pk_mul_f32 v[22:23], v[54:55], v[24:25]
	v_pk_mul_f32 v[56:57], v[136:137], v[56:57]
	v_add_f32_e32 v24, v23, v22
	v_pk_mul_f32 v[22:23], v[140:141], v[18:19] op_sel:[1,0] op_sel_hi:[0,1]
	v_pk_mul_f32 v[18:19], v[140:141], v[18:19]
	v_sub_f32_e32 v22, v22, v23
	v_add_f32_e32 v23, v19, v18
	v_pk_mul_f32 v[18:19], v[56:57], v[20:21] op_sel:[1,0] op_sel_hi:[0,1]
	v_sub_f32_e32 v25, v18, v19
	v_pk_mul_f32 v[18:19], v[56:57], v[20:21]
	v_mov_b32_e32 v113, v131
	v_add_f32_e32 v20, v19, v18
	v_pk_mul_f32 v[18:19], v[138:139], v[14:15] op_sel:[1,0] op_sel_hi:[0,1]
	v_pk_mul_f32 v[14:15], v[138:139], v[14:15]
	v_sub_f32_e32 v18, v18, v19
	v_add_f32_e32 v19, v15, v14
	v_pk_mul_f32 v[14:15], v[50:51], v[16:17] op_sel:[1,0] op_sel_hi:[0,1]
	v_sub_f32_e32 v21, v14, v15
	v_pk_mul_f32 v[14:15], v[50:51], v[16:17]
	v_mov_b32_e32 v99, v131
	v_add_f32_e32 v16, v15, v14
	v_pk_mul_f32 v[14:15], v[126:127], v[10:11] op_sel:[1,0] op_sel_hi:[0,1]
	v_pk_mul_f32 v[10:11], v[126:127], v[10:11]
	v_cvt_pk_fp8_f32 v113, v19, v16
	v_sub_f32_e32 v14, v14, v15
	v_add_f32_e32 v15, v11, v10
	v_pk_mul_f32 v[10:11], v[52:53], v[12:13] op_sel:[1,0] op_sel_hi:[0,1]
	v_sub_f32_e32 v17, v10, v11
	v_pk_mul_f32 v[10:11], v[52:53], v[12:13]
	v_add_u32_e32 v157, 0, v208
	v_add_u32_e32 v158, 0, v207
	v_add_f32_e32 v10, v11, v10
	v_cvt_pk_fp8_f32 v99, v74, v77
	ds_write_b128 v157, v[6:9] offset:24576
	ds_write_b128 v158, v[2:5]
	v_lshlrev_b32_e32 v74, 1, v205
	v_lshrrev_b32_e32 v2, 1, v209
	v_cvt_pk_fp8_f32 v113, v15, v10 op_sel:[0,0,1]
	v_bfe_u32 v10, v209, 1, 3
	v_bitop3_b32 v2, v74, v2, 7 bitop3:0x78
	v_lshlrev_b32_e32 v159, 4, v2
	v_bitop3_b32 v2, v74, v10, 1 bitop3:0x36
	v_mov_b32_e32 v100, v131
	v_mov_b32_e32 v103, v131
	v_mov_b32_e32 v104, v131
	v_lshlrev_b32_e32 v154, 7, v203
	v_lshlrev_b32_e32 v160, 4, v2
	v_cvt_pk_fp8_f32 v100, v66, v69
	v_cvt_pk_fp8_f32 v103, v75, v72
	v_cvt_pk_fp8_f32 v104, v67, v64
	v_add3_u32 v6, 0, v159, v154
	v_add3_u32 v11, 0, v160, v154
	v_mov_b32_e32 v98, v131
	v_mov_b32_e32 v102, v131
	s_waitcnt lgkmcnt(0)
	s_barrier
	ds_read_b128 v[2:5], v6 offset:24576
	ds_read_b128 v[50:53], v6 offset:28672
	ds_read_b128 v[6:9], v11 offset:24576
	ds_read_b128 v[54:57], v11 offset:28672
	v_bitop3_b32 v11, v74, v10, 4 bitop3:0x36
	v_cvt_pk_fp8_f32 v98, v106, v108
	v_mov_b32_e32 v101, v131
	v_cvt_pk_fp8_f32 v102, v107, v84
	v_mov_b32_e32 v105, v131
	v_mov_b32_e32 v106, v131
	v_mov_b32_e32 v107, v131
	v_mov_b32_e32 v108, v131
	v_mov_b32_e32 v109, v131
	v_mov_b32_e32 v110, v131
	v_mov_b32_e32 v111, v131
	v_mov_b32_e32 v112, v131
	v_lshlrev_b32_e32 v161, 4, v11
	v_bitop3_b32 v10, v74, v10, 5 bitop3:0x36
	v_cvt_pk_fp8_f32 v101, v58, v61
	v_cvt_pk_fp8_f32 v105, v59, v48
	v_cvt_pk_fp8_f32 v106, v42, v45
	v_cvt_pk_fp8_f32 v107, v34, v37
	v_cvt_pk_fp8_f32 v108, v26, v29
	v_cvt_pk_fp8_f32 v109, v18, v21
	v_cvt_pk_fp8_f32 v110, v43, v40
	v_cvt_pk_fp8_f32 v111, v35, v32
	v_cvt_pk_fp8_f32 v112, v27, v24
	v_add3_u32 v11, 0, v161, v154
	v_lshlrev_b32_e32 v162, 4, v10
	v_cvt_pk_fp8_f32 v99, v70, v73 op_sel:[0,0,1]
	v_cvt_pk_fp8_f32 v100, v62, v65 op_sel:[0,0,1]
	v_cvt_pk_fp8_f32 v103, v71, v68 op_sel:[0,0,1]
	v_cvt_pk_fp8_f32 v104, v63, v60 op_sel:[0,0,1]
	v_add3_u32 v10, 0, v162, v154
	ds_read_b128 v[58:61], v11 offset:24576
	ds_read_b128 v[66:69], v11 offset:28672
	ds_read_b128 v[62:65], v10 offset:24576
	ds_read_b128 v[70:73], v10 offset:28672
	v_cvt_pk_fp8_f32 v98, v82, v85 op_sel:[0,0,1]
	v_cvt_pk_fp8_f32 v101, v46, v49 op_sel:[0,0,1]
	v_cvt_pk_fp8_f32 v102, v83, v76 op_sel:[0,0,1]
	v_cvt_pk_fp8_f32 v105, v47, v44 op_sel:[0,0,1]
	v_cvt_pk_fp8_f32 v106, v38, v41 op_sel:[0,0,1]
	v_cvt_pk_fp8_f32 v107, v30, v33 op_sel:[0,0,1]
	v_cvt_pk_fp8_f32 v108, v22, v25 op_sel:[0,0,1]
	v_cvt_pk_fp8_f32 v109, v14, v17 op_sel:[0,0,1]
	v_cvt_pk_fp8_f32 v110, v39, v36 op_sel:[0,0,1]
	v_cvt_pk_fp8_f32 v111, v31, v28 op_sel:[0,0,1]
	v_cvt_pk_fp8_f32 v112, v23, v20 op_sel:[0,0,1]
	s_nop 1
	s_setprio 1
	s_mov_b32 s53, s52
	s_mov_b32 s54, s52
	s_mov_b32 s55, s52
	s_mov_b32 s56, s52
	s_mov_b32 s57, s52
	s_mov_b32 s58, s52
	s_mov_b32 s59, s52
	s_mov_b32 s60, s52
	s_mov_b32 s61, s52
	s_mov_b32 s62, s52
	s_mov_b32 s63, s52
	s_mov_b32 s64, s52
	s_mov_b32 s65, s52
	s_mov_b32 s66, s52
	s_mov_b32 s67, s52
	v_mov_b64_e32 v[34:35], s[52:53]
	v_mov_b64_e32 v[36:37], s[54:55]
	v_mov_b64_e32 v[38:39], s[56:57]
	v_mov_b64_e32 v[40:41], s[58:59]
	v_mov_b64_e32 v[42:43], s[60:61]
	v_mov_b64_e32 v[44:45], s[62:63]
	v_mov_b64_e32 v[46:47], s[64:65]
	v_mov_b64_e32 v[48:49], s[66:67]
	v_mov_b64_e32 v[18:19], v[34:35]
	v_mov_b64_e32 v[20:21], v[36:37]
	v_mov_b64_e32 v[22:23], v[38:39]
	v_mov_b64_e32 v[24:25], v[40:41]
	v_mov_b64_e32 v[26:27], v[42:43]
	v_mov_b64_e32 v[28:29], v[44:45]
	v_mov_b64_e32 v[30:31], v[46:47]
	v_mov_b64_e32 v[32:33], v[48:49]
	s_waitcnt lgkmcnt(5)
	v_mfma_scale_f32_32x32x64_f8f6f4 v[18:33], v[2:9], v[98:105], v[18:33], v133, v133 op_sel_hi:[0,0,0]
	v_mov_b32_e32 v2, v131
	v_mov_b32_e32 v3, v131
	v_mov_b32_e32 v4, v131
	v_mov_b32_e32 v5, v131
	v_mov_b32_e32 v6, v131
	v_mov_b32_e32 v7, v131
	v_mov_b32_e32 v8, v131
	v_mov_b32_e32 v9, v131
	v_mov_b32_e32 v10, v131
	v_mov_b32_e32 v11, v131
	v_mov_b32_e32 v12, v131
	v_mov_b32_e32 v13, v131
	v_mov_b32_e32 v14, v131
	v_mov_b32_e32 v15, v131
	v_mov_b32_e32 v16, v131
	v_mov_b32_e32 v17, v131
	s_waitcnt lgkmcnt(4)
	v_mfma_scale_f32_32x32x64_f8f6f4 v[34:49], v[50:57], v[98:105], v[34:49], v133, v133 op_sel_hi:[0,0,0]
	s_waitcnt lgkmcnt(1)
; #define SLOAD8(i, t) do { sk[i] = *reinterpret_cast<const i32x4a*>(kg + (long)(t) * (64 * 512)); sv[i] = *reinterpret_cast<const i32x4a*>(vg + (long)(t) * VT_STRIDE); } while (0)
; #define SWRITE8(b, i) do { *reinterpret_cast<ATT_LAS i32x4a*>(K_lds + (b) * 8192 + kst) = sk[i]; *reinterpret_cast<ATT_LAS i32x4a*>(V_lds + (b) * 8192 + vst) = sv[i]; } while (0)
; #define SWAIT8() asm volatile("s_waitcnt vmcnt(2)" ::: "memory")
; __device__ __forceinline__ void partialSM8(f32x16& p0, f32x16& p1, float& m_reg, float& mn, float& alpha) {
;   constexpr float C = SCALE * 1.4426950408889634f;
;   float pmax = p0[0];
; #pragma unroll
;   for (int r = 1; r < 16; ++r) pmax = fmaxf(pmax, p0[r]);
; #pragma unroll
;   for (int r = 0; r < 16; ++r) pmax = fmaxf(pmax, p1[r]);
;   { auto rr = __builtin_amdgcn_permlane32_swap(__float_as_uint(pmax), __float_as_uint(pmax), false, false);
;     pmax = fmaxf(__uint_as_float(rr[0]), __uint_as_float(rr[1])); }
;   if (__builtin_expect(__all(pmax - m_reg <= THR8 / SCALE), 1)) { mn = m_reg; alpha = 1.f; }
;   else { mn = fmaxf(m_reg, pmax); alpha = __builtin_amdgcn_exp2f((m_reg - mn) * C); m_reg = mn; }
;   float mnC = -mn * C;
; #pragma unroll
;   for (int r = 0; r < 16; ++r) p0[r] = fmaf(p0[r], C, mnC);
; #pragma unroll
;   for (int r = 0; r < 16; ++r) p1[r] = fmaf(p1[r], C, mnC);
; #pragma unroll
;   for (int r = 0; r < 16; ++r) p0[r] = __builtin_amdgcn_exp2f(p0[r]);
; __device__ __forceinline__ void attn_unit8(const bf16_t* __restrict__ Qb, const unsigned char* __restrict__ K8h, const unsigned char* __restrict__ VT8h, unsigned char* __restrict__ Ob, int seq, ATT_LAS char* lds, ...
;     ...
;   qkt8<true>(pA0, pA1, K_lds, q8, r32, hi, one); partialSM8(pA0, pA1, m_reg, mnA, alA);
;   SLOAD8(1, 1); if (2 < NT) SLOAD8(0, 2);
;   SWAIT8(); SWRITE8(1, 1); __syncthreads();
;   int bK = 8192, bV = 0, bW = 2 * 8192;
	v_mfma_scale_f32_32x32x64_f8f6f4 v[18:33], v[58:65], v[106:113], v[18:33], v133, v133 op_sel_hi:[0,0,0]
	s_waitcnt lgkmcnt(0)
	v_mfma_scale_f32_32x32x64_f8f6f4 v[34:49], v[66:73], v[106:113], v[34:49], v133, v133 op_sel_hi:[0,0,0]
	s_setprio 0
	v_add_co_u32_e32 v50, vcc, s70, v118
	s_nop 15
	s_nop 7
	v_max_f32_e32 v62, v19, v19
	s_nop 0
	v_addc_co_u32_e32 v51, vcc, 0, v119, vcc
	v_add_co_u32_e32 v54, vcc, s70, v120
	v_max_f32_e32 v63, v18, v18
	s_nop 0
	v_addc_co_u32_e32 v55, vcc, 0, v121, vcc
	v_add_co_u32_e32 v58, vcc, s71, v120
	global_load_dwordx4 v[50:53], v[50:51], off
	s_nop 0
	global_load_dwordx4 v[54:57], v[54:55], off
	v_addc_co_u32_e32 v59, vcc, 0, v121, vcc
	v_add_co_u32_e32 v60, vcc, s71, v118
	v_max_f32_e32 v62, v63, v62
	s_nop 0
	v_addc_co_u32_e32 v61, vcc, 0, v119, vcc
	global_load_dwordx4 v[114:117], v[58:59], off
	global_load_dwordx4 v[118:121], v[60:61], off
	v_max3_f32 v58, v62, v20, v21
	v_max3_f32 v58, v58, v22, v23
	v_max3_f32 v58, v58, v24, v25
	v_max3_f32 v58, v58, v26, v27
	v_max3_f32 v58, v58, v28, v29
	v_max3_f32 v58, v58, v30, v31
	v_max3_f32 v58, v58, v32, v33
	v_max3_f32 v58, v58, v34, v35
	v_max3_f32 v58, v58, v36, v37
	v_max3_f32 v58, v58, v38, v39
	v_max3_f32 v58, v58, v40, v41
	v_max3_f32 v58, v58, v42, v43
	v_max3_f32 v58, v58, v44, v45
	v_max3_f32 v58, v58, v46, v47
	v_max3_f32 v58, v58, v48, v49
	v_mov_b32_e32 v59, v58
	s_nop 1
	v_permlane32_swap_b32_e32 v58, v59
	v_max_f32_e32 v59, v59, v59
	v_max_f32_e32 v58, v58, v58
	v_max_f32_e32 v58, v58, v59
	v_add_f32_e32 v59, 0x7149f2ca, v58
	v_cmp_ge_f32_e32 vcc, s69, v59
	s_cmp_eq_u64 vcc, exec
	v_max_f32_e32 v58, 0xf149f2ca, v58
	s_cselect_b64 vcc, -1, 0
	v_cndmask_b32_e32 v167, v58, v202, vcc
	v_sub_f32_e32 v60, 0xf149f2ca, v58
	v_mul_f32_e32 v58, 0xbe0293ee, v167
	v_fmamk_f32 v18, v18, 0x3e0293ee, v58
	v_exp_f32_e32 v176, v18
	v_fmamk_f32 v18, v24, 0x3e0293ee, v58
	v_exp_f32_e32 v174, v18
	v_fmamk_f32 v18, v25, 0x3e0293ee, v58
	v_exp_f32_e32 v175, v18
	v_fmamk_f32 v18, v26, 0x3e0293ee, v58
	v_exp_f32_e32 v182, v18
	v_fmamk_f32 v18, v27, 0x3e0293ee, v58
	v_exp_f32_e32 v184, v18
	v_fmamk_f32 v18, v28, 0x3e0293ee, v58
	v_exp_f32_e32 v178, v18
	v_fmamk_f32 v18, v29, 0x3e0293ee, v58
	v_exp_f32_e32 v181, v18
	v_fmamk_f32 v18, v30, 0x3e0293ee, v58
	v_mul_f32_e32 v60, 0x3e0293ee, v60
	v_exp_f32_e32 v185, v18
	v_fmamk_f32 v18, v31, 0x3e0293ee, v58
	v_exp_f32_e32 v60, v60
	v_exp_f32_e32 v187, v18
	v_fmamk_f32 v18, v32, 0x3e0293ee, v58
	s_add_u32 s8, s25, s8
	v_pk_fma_f32 v[126:127], v[48:49], s[16:17], v[58:59] op_sel_hi:[1,0,0]
	v_pk_fma_f32 v[128:129], v[46:47], s[16:17], v[58:59] op_sel_hi:[1,0,0]
	v_pk_fma_f32 v[140:141], v[44:45], s[16:17], v[58:59] op_sel_hi:[1,0,0]
	v_pk_fma_f32 v[142:143], v[42:43], s[16:17], v[58:59] op_sel_hi:[1,0,0]
	v_pk_fma_f32 v[144:145], v[40:41], s[16:17], v[58:59] op_sel_hi:[1,0,0]
	v_pk_fma_f32 v[146:147], v[38:39], s[16:17], v[58:59] op_sel_hi:[1,0,0]
	v_pk_fma_f32 v[148:149], v[36:37], s[16:17], v[58:59] op_sel_hi:[1,0,0]
	v_pk_fma_f32 v[150:151], v[34:35], s[16:17], v[58:59] op_sel_hi:[1,0,0]
	v_fmamk_f32 v19, v19, 0x3e0293ee, v58
	v_fmamk_f32 v20, v20, 0x3e0293ee, v58
	v_fmamk_f32 v21, v21, 0x3e0293ee, v58
	v_fmamk_f32 v22, v22, 0x3e0293ee, v58
	v_fmamk_f32 v23, v23, 0x3e0293ee, v58
	v_exp_f32_e32 v183, v18
	v_fmac_f32_e32 v58, 0x3e0293ee, v33
	v_lshrrev_b32_e32 v18, 2, v209
	s_addc_u32 s9, 0, s9
	v_exp_f32_e32 v179, v19
	v_exp_f32_e32 v172, v20
	v_exp_f32_e32 v173, v21
	v_exp_f32_e32 v177, v22
	v_exp_f32_e32 v180, v23
	v_exp_f32_e32 v186, v58
	v_bfe_u32 v19, v209, 2, 2
	v_bitop3_b32 v18, v74, v18, 3 bitop3:0x78
	v_lshl_add_u64 v[136:137], s[8:9], 0, v[124:125]
	s_add_i32 s8, s26, s24
	s_waitcnt vmcnt(2)
	v_lshlrev_b32_e32 v164, 4, v18
	v_bitop3_b32 v18, v74, v19, 1 bitop3:0x36
	s_ashr_i32 s9, s8, 31
	v_cndmask_b32_e64 v166, v60, 1.0, vcc
	s_waitcnt vmcnt(0) lgkmcnt(0)
	ds_write_b128 v157, v[50:53] offset:32768
	ds_write_b128 v158, v[54:57] offset:8192
	v_lshlrev_b32_e32 v165, 4, v18
	s_lshl_b64 s[8:9], s[8:9], 13
	v_mov_b64_e32 v[64:65], v[16:17]
	v_mov_b64_e32 v[48:49], v[16:17]
	v_mov_b64_e32 v[32:33], v[16:17]
	v_lshlrev_b32_e32 v163, 6, v203
	v_cmp_gt_u32_e64 s[6:7], 32, v135
	v_lshl_add_u32 v152, v203, 2, v206
	v_or_b32_e32 v136, v136, v130
	v_lshl_add_u64 v[138:139], s[8:9], 0, v[122:123]
	v_mov_b32_e32 v153, 0
	s_movk_i32 s53, 0x2000
	s_movk_i32 s8, 0x4000
	v_mov_b64_e32 v[62:63], v[14:15]
	v_mov_b64_e32 v[60:61], v[12:13]
	v_mov_b64_e32 v[58:59], v[10:11]
	v_mov_b64_e32 v[56:57], v[8:9]
	v_mov_b64_e32 v[54:55], v[6:7]
	v_mov_b64_e32 v[52:53], v[4:5]
	v_mov_b64_e32 v[50:51], v[2:3]
	v_mov_b64_e32 v[46:47], v[14:15]
	v_mov_b64_e32 v[44:45], v[12:13]
	v_mov_b64_e32 v[42:43], v[10:11]
	v_mov_b64_e32 v[40:41], v[8:9]
	v_mov_b64_e32 v[38:39], v[6:7]
	v_mov_b64_e32 v[36:37], v[4:5]
	v_mov_b64_e32 v[34:35], v[2:3]
	v_mov_b64_e32 v[30:31], v[14:15]
	v_mov_b64_e32 v[28:29], v[12:13]
	v_mov_b64_e32 v[26:27], v[10:11]
	v_mov_b64_e32 v[24:25], v[8:9]
	v_mov_b64_e32 v[22:23], v[6:7]
	v_mov_b64_e32 v[20:21], v[4:5]
	v_mov_b64_e32 v[18:19], v[2:3]
	s_waitcnt lgkmcnt(0)
	s_barrier
; #define SBAR() __builtin_amdgcn_sched_barrier(0)
; __device__ __forceinline__ unsigned pk4f8(float a, float b, float c, float d) { unsigned w = 0u; w = __builtin_amdgcn_cvt_pk_fp8_f32(a, b, w, false); w = __builtin_amdgcn_cvt_pk_fp8_f32(c, d, w, true); return w; }
; #define SLOAD8(i, t) do { sk[i] = *reinterpret_cast<const i32x4a*>(kg + (long)(t) * (64 * 512)); sv[i] = *reinterpret_cast<const i32x4a*>(vg + (long)(t) * VT_STRIDE); } while (0)
; #define SWAIT8() asm volatile("s_waitcnt vmcnt(2)" ::: "memory")
; #define SWRITE8R(boff, i) do { *reinterpret_cast<ATT_LAS i32x4a*>(K_lds + (boff) + kst) = sk[i]; *reinterpret_cast<ATT_LAS i32x4a*>(V_lds + (boff) + vst) = sv[i]; } while (0)
; __device__ __forceinline__ void finishSM8(f32x16& p0, f32x16& p1, float alpha, float& l_reg, i32x8a& pa) {
; #pragma unroll
;   for (int r = 0; r < 16; ++r) p1[r] = __builtin_amdgcn_exp2f(p1[r]);
;   float ps = 0;
; #pragma unroll
;   for (int r = 0; r < 16; ++r) ps += p0[r];
; #pragma unroll
;   for (int r = 0; r < 16; ++r) ps += p1[r];
;   { auto rr = __builtin_amdgcn_permlane32_swap(__float_as_uint(ps), __float_as_uint(ps), false, false);
;     ps = __uint_as_float(rr[0]) + __uint_as_float(rr[1]); }
;   l_reg = l_reg * alpha + ps;
;   pa = (i32x8a){(int)pk4f8(p0[0], p0[1], p0[2], p0[3]), (int)pk4f8(p0[4], p0[5], p0[6], p0[7]), (int)pk4f8(p0[8], p0[9], p0[10], p0[11]), (int)pk4f8(p0[12], p0[13], p0[14], p0[15]),
;                 (int)pk4f8(p1[0], p1[1], p1[2], p1[3]), (int)pk4f8(p1[4], p1[5], p1[6], p1[7]), (int)pk4f8(p1[8], p1[9], p1[10], p1[11]), (int)pk4f8(p1[12], p1[13], p1[14], p1[15])};
; }
; __device__ __forceinline__ void attn_unit8(const bf16_t* __restrict__ Qb, const unsigned char* __restrict__ K8h, const unsigned char* __restrict__ VT8h, unsigned char* __restrict__ Ob, int seq, ATT_LAS char* lds, ...
;     ...
;     SBAR(); qkt8<false>(pB0, pB1, K_lds + bK, q8, r32, hi, one);
;     finishSM8(pA0, pA1, alA, l_reg, pa); SBAR();
;     SLOAD8(1, j + 2); SBAR();
;     pv8<false>(o, V_lds + bV, pa, r32, hi, one); partialSM8(pB0, pB1, m_reg, mnB, alB);
;     SWAIT8(); SWRITE8R(bW, 0);
;     RESC8(alB); __syncthreads();
.LBB0_549:
	s_mov_b32 s54, s52
	s_mov_b32 s52, s8
	s_add_i32 s26, s53, 0
	v_add3_u32 v66, s26, v159, v154
	v_add3_u32 v67, s26, v160, v154
	ds_read_b128 v[188:191], v66 offset:24576
	ds_read_b128 v[210:213], v66 offset:28672
	ds_read_b128 v[192:195], v67 offset:24576
	ds_read_b128 v[214:217], v67 offset:28672
	v_add3_u32 v66, s26, v161, v154
	v_add3_u32 v67, s26, v162, v154
	ds_read_b128 v[218:221], v66 offset:24576
	ds_read_b128 v[226:229], v66 offset:28672
	ds_read_b128 v[222:225], v67 offset:24576
	ds_read_b128 v[230:233], v67 offset:28672
	s_nop 1
	s_setprio 1
	v_mov_b64_e32 v[80:81], s[50:51]
	v_mov_b64_e32 v[78:79], s[48:49]
	v_mov_b64_e32 v[76:77], s[46:47]
	v_mov_b64_e32 v[74:75], s[44:45]
	v_mov_b64_e32 v[72:73], s[42:43]
	v_mov_b64_e32 v[70:71], s[40:41]
	v_mov_b64_e32 v[68:69], s[38:39]
	v_mov_b64_e32 v[66:67], s[36:37]
	v_mov_b64_e32 v[96:97], v[80:81]
	v_mov_b64_e32 v[94:95], v[78:79]
	v_mov_b64_e32 v[92:93], v[76:77]
	v_mov_b64_e32 v[90:91], v[74:75]
	v_mov_b64_e32 v[88:89], v[72:73]
	v_mov_b64_e32 v[86:87], v[70:71]
	v_mov_b64_e32 v[84:85], v[68:69]
	v_mov_b64_e32 v[82:83], v[66:67]
	s_waitcnt lgkmcnt(5)
	v_mfma_scale_f32_32x32x64_f8f6f4 v[82:97], v[188:195], v[98:105], v[82:97], v133, v133 op_sel_hi:[0,0,0]
	s_waitcnt lgkmcnt(4)
	v_mfma_scale_f32_32x32x64_f8f6f4 v[66:81], v[210:217], v[98:105], v[66:81], v133, v133 op_sel_hi:[0,0,0]
	s_waitcnt lgkmcnt(1)
	v_mfma_scale_f32_32x32x64_f8f6f4 v[82:97], v[218:225], v[106:113], v[82:97], v133, v133 op_sel_hi:[0,0,0]
	s_waitcnt lgkmcnt(0)
	v_mfma_scale_f32_32x32x64_f8f6f4 v[66:81], v[226:233], v[106:113], v[66:81], v133, v133 op_sel_hi:[0,0,0]
	s_setprio 0
	v_exp_f32_e32 v155, v144
	v_add_f32_e32 v144, 0, v176
	v_add_f32_e32 v144, v179, v144
	v_add_f32_e32 v144, v172, v144
	v_add_f32_e32 v144, v173, v144
	v_add_f32_e32 v144, v177, v144
	v_add_f32_e32 v144, v180, v144
	v_add_f32_e32 v144, v174, v144
	v_add_f32_e32 v144, v175, v144
	v_add_f32_e32 v144, v182, v144
	v_add_f32_e32 v144, v184, v144
	v_add_f32_e32 v144, v178, v144
	v_add_f32_e32 v144, v181, v144
	v_exp_f32_e32 v122, v150
	v_add_f32_e32 v144, v185, v144
	v_exp_f32_e32 v123, v151
	v_add_f32_e32 v144, v187, v144
	v_exp_f32_e32 v124, v148
	v_add_f32_e32 v144, v183, v144
	v_exp_f32_e32 v125, v149
	v_add_f32_e32 v144, v186, v144
	v_exp_f32_e32 v150, v146
	v_add_f32_e32 v144, v122, v144
	v_exp_f32_e32 v151, v147
	v_add_f32_e32 v144, v123, v144
	v_add_f32_e32 v144, v124, v144
	v_exp_f32_e32 v156, v145
	v_add_f32_e32 v144, v125, v144
	v_exp_f32_e32 v142, v142
	v_add_f32_e32 v144, v150, v144
	v_exp_f32_e32 v143, v143
	v_add_f32_e32 v144, v151, v144
	v_exp_f32_e32 v140, v140
	v_add_f32_e32 v144, v155, v144
	v_exp_f32_e32 v141, v141
	v_add_f32_e32 v144, v156, v144
	v_exp_f32_e32 v128, v128
	v_add_f32_e32 v144, v142, v144
	v_exp_f32_e32 v129, v129
	v_add_f32_e32 v144, v143, v144
	v_exp_f32_e32 v126, v126
	v_add_f32_e32 v144, v140, v144
	v_exp_f32_e32 v127, v127
	v_add_f32_e32 v144, v141, v144
	v_add_f32_e32 v144, v128, v144
	v_add_f32_e32 v144, v129, v144
	v_add_f32_e32 v144, v126, v144
	v_add_f32_e32 v169, v127, v144
	v_mov_b32_e32 v144, 0
	v_cvt_pk_fp8_f32 v144, v176, v179
	v_mov_b32_e32 v149, 0
	v_mov_b32_e32 v145, 0
	v_mov_b32_e32 v146, 0
	v_mov_b32_e32 v147, 0
	v_mov_b32_e32 v148, 0
	v_cvt_pk_fp8_f32 v149, v150, v151
	v_mov_b32_e32 v150, 0
	v_mov_b32_e32 v151, 0
	v_cvt_pk_fp8_f32 v145, v177, v180
	v_cvt_pk_fp8_f32 v146, v182, v184
	v_cvt_pk_fp8_f32 v147, v185, v187
	v_cvt_pk_fp8_f32 v144, v172, v173 op_sel:[0,0,1]
	v_cvt_pk_fp8_f32 v148, v122, v123
	v_cvt_pk_fp8_f32 v150, v142, v143
	v_cvt_pk_fp8_f32 v151, v128, v129
	v_mov_b32_e32 v170, v169
	s_nop 1
	v_permlane32_swap_b32_e32 v169, v170
	v_cvt_pk_fp8_f32 v145, v174, v175 op_sel:[0,0,1]
	v_cvt_pk_fp8_f32 v146, v178, v181 op_sel:[0,0,1]
	v_cvt_pk_fp8_f32 v147, v183, v186 op_sel:[0,0,1]
	v_cvt_pk_fp8_f32 v148, v124, v125 op_sel:[0,0,1]
	v_cvt_pk_fp8_f32 v149, v155, v156 op_sel:[0,0,1]
	v_cvt_pk_fp8_f32 v150, v140, v141 op_sel:[0,0,1]
	v_cvt_pk_fp8_f32 v151, v126, v127 op_sel:[0,0,1]
	v_lshl_add_u64 v[142:143], s[10:11], 0, v[136:137]
	v_add_co_u32_e32 v122, vcc, s74, v142
	v_lshl_add_u64 v[140:141], s[10:11], 0, v[138:139]
	s_nop 0
	v_addc_co_u32_e32 v123, vcc, 0, v143, vcc
	v_add_co_u32_e32 v126, vcc, s75, v140
	s_nop 1
	v_addc_co_u32_e32 v127, vcc, 0, v141, vcc
	global_load_dwordx4 v[122:125], v[122:123], off
	s_nop 0
	global_load_dwordx4 v[126:129], v[126:127], off
	s_add_i32 s56, s54, 0
	v_add_u32_e32 v155, s56, v164
	v_add_u32_e32 v155, v155, v163
	v_add_u32_e32 v156, s56, v165
	v_add_u32_e32 v156, v156, v163
	ds_read_b128 v[172:175], v155
	ds_read_b128 v[180:183], v155 offset:2048
	ds_read_b128 v[176:179], v156
	ds_read_b128 v[184:187], v156 offset:2048
	ds_read_b128 v[188:191], v155 offset:4096
	ds_read_b128 v[210:213], v155 offset:6144
	ds_read_b128 v[192:195], v156 offset:4096
	ds_read_b128 v[214:217], v156 offset:6144
	s_setprio 1
	s_waitcnt lgkmcnt(0)
	v_mfma_scale_f32_32x32x64_f8f6f4 v[2:17], v[144:151], v[172:179], v[2:17], v133, v133 op_sel_hi:[0,0,0]
	v_mfma_scale_f32_32x32x64_f8f6f4 v[50:65], v[144:151], v[180:187], v[50:65], v133, v133 op_sel_hi:[0,0,0]
	v_mfma_scale_f32_32x32x64_f8f6f4 v[34:49], v[144:151], v[188:195], v[34:49], v133, v133 op_sel_hi:[0,0,0]
	v_mfma_scale_f32_32x32x64_f8f6f4 v[18:33], v[144:151], v[210:217], v[18:33], v133, v133 op_sel_hi:[0,0,0]
	s_setprio 0
	v_max_f32_e32 v144, v83, v83
	v_max_f32_e32 v145, v82, v82
	v_max_f32_e32 v144, v145, v144
	v_max3_f32 v144, v144, v84, v85
	v_max3_f32 v144, v144, v86, v87
	v_max3_f32 v144, v144, v88, v89
	v_max3_f32 v144, v144, v90, v91
	v_max3_f32 v144, v144, v92, v93
	v_max3_f32 v144, v144, v94, v95
	v_max3_f32 v144, v144, v96, v97
	v_max3_f32 v144, v144, v66, v67
	v_max3_f32 v144, v144, v68, v69
	v_max3_f32 v144, v144, v70, v71
	v_max3_f32 v144, v144, v72, v73
	v_max3_f32 v144, v144, v74, v75
	v_max3_f32 v144, v144, v76, v77
	v_max3_f32 v144, v144, v78, v79
	v_max3_f32 v144, v144, v80, v81
	v_mov_b32_e32 v145, v144
	s_nop 1
	v_permlane32_swap_b32_e32 v144, v145
	v_max_f32_e32 v145, v145, v145
	v_max_f32_e32 v144, v144, v144
	v_max_f32_e32 v144, v144, v145
	v_max_f32_e32 v146, v167, v167
	v_sub_f32_e32 v145, v144, v167
	v_max_f32_e32 v144, v146, v144
	v_sub_f32_e32 v146, v167, v144
	v_mul_f32_e32 v146, 0x3e0293ee, v146
	v_exp_f32_e32 v146, v146
	v_cmp_ge_f32_e32 vcc, s69, v145
	s_cmp_eq_u64 vcc, exec
	s_cselect_b64 s[8:9], -1, 0
	s_waitcnt vmcnt(2)
	s_add_i32 s55, s52, 0
	v_cndmask_b32_e64 v171, v146, 1.0, s[8:9]
	v_add_u32_e32 v145, s55, v208
	ds_write_b128 v145, v[118:121] offset:24576
	v_add_u32_e32 v145, s52, v158
	v_cmp_gt_f32_e32 vcc, 1.0, v171
	ds_write_b128 v145, v[114:117]
	s_cbranch_vccz .LBB0_553
; #define SBAR() __builtin_amdgcn_sched_barrier(0)
; #define SLOAD8(i, t) do { sk[i] = *reinterpret_cast<const i32x4a*>(kg + (long)(t) * (64 * 512)); sv[i] = *reinterpret_cast<const i32x4a*>(vg + (long)(t) * VT_STRIDE); } while (0)
; __device__ __forceinline__ void attn_unit8(const bf16_t* __restrict__ Qb, const unsigned char* __restrict__ K8h, const unsigned char* __restrict__ VT8h, unsigned char* __restrict__ Ob, int seq, ATT_LAS char* lds, ...
;     ...
;     { const int t = bV; bV = bK; bK = bW; bW = t; }
;     SBAR(); qkt8<false>(pA0, pA1, K_lds + bK, q8, r32, hi, one);
;     finishSM8(pB0, pB1, alB, l_reg, pa); SBAR();
;     if (j + 3 < NT) SLOAD8(0, j + 3); SBAR();
	s_and_saveexec_b64 s[24:25], s[6:7]
	ds_write_b32 v152, v171 offset:49280
	s_or_b64 exec, exec, s[24:25]
	s_waitcnt lgkmcnt(0)
	v_add_u32_e32 v145, v206, v134
	ds_read_b128 v[146:149], v145 offset:49376
	ds_read_b128 v[172:175], v145 offset:49344
	ds_read_b128 v[176:179], v145 offset:49312
	ds_read_b128 v[180:183], v145 offset:49280
	s_waitcnt lgkmcnt(0)
	v_pk_mul_f32 v[14:15], v[14:15], v[146:147]
	v_pk_mul_f32 v[10:11], v[10:11], v[172:173]
	v_pk_mul_f32 v[6:7], v[6:7], v[176:177]
	v_pk_mul_f32 v[16:17], v[16:17], v[148:149]
	v_pk_mul_f32 v[12:13], v[12:13], v[174:175]
	v_pk_mul_f32 v[8:9], v[8:9], v[178:179]
	v_pk_mul_f32 v[4:5], v[4:5], v[182:183]
	v_pk_mul_f32 v[2:3], v[2:3], v[180:181]
	v_pk_mul_f32 v[62:63], v[62:63], v[146:147]
	v_pk_mul_f32 v[58:59], v[58:59], v[172:173]
	v_pk_mul_f32 v[54:55], v[54:55], v[176:177]
	v_pk_mul_f32 v[64:65], v[64:65], v[148:149]
	v_pk_mul_f32 v[60:61], v[60:61], v[174:175]
	v_pk_mul_f32 v[56:57], v[56:57], v[178:179]
	v_pk_mul_f32 v[52:53], v[52:53], v[182:183]
	v_pk_mul_f32 v[50:51], v[50:51], v[180:181]
	v_pk_mul_f32 v[46:47], v[46:47], v[146:147]
	v_pk_mul_f32 v[42:43], v[42:43], v[172:173]
	v_pk_mul_f32 v[38:39], v[38:39], v[176:177]
	v_pk_mul_f32 v[48:49], v[48:49], v[148:149]
	v_pk_mul_f32 v[44:45], v[44:45], v[174:175]
	v_pk_mul_f32 v[40:41], v[40:41], v[178:179]
	v_pk_mul_f32 v[36:37], v[36:37], v[182:183]
	v_pk_mul_f32 v[34:35], v[34:35], v[180:181]
	v_pk_mul_f32 v[30:31], v[30:31], v[146:147]
	v_pk_mul_f32 v[26:27], v[26:27], v[172:173]
	v_pk_mul_f32 v[22:23], v[22:23], v[176:177]
	v_pk_mul_f32 v[32:33], v[32:33], v[148:149]
	v_pk_mul_f32 v[28:29], v[28:29], v[174:175]
	v_pk_mul_f32 v[24:25], v[24:25], v[178:179]
	v_pk_mul_f32 v[20:21], v[20:21], v[182:183]
	v_pk_mul_f32 v[18:19], v[18:19], v[180:181]
.LBB0_553:
	v_cndmask_b32_e64 v144, v144, v167, s[8:9]
	v_mul_f32_e32 v197, 0xbe0293ee, v144
	v_fmamk_f32 v82, v82, 0x3e0293ee, v197
	v_fmamk_f32 v83, v83, 0x3e0293ee, v197
	v_fmamk_f32 v84, v84, 0x3e0293ee, v197
	v_fmamk_f32 v85, v85, 0x3e0293ee, v197
	v_fmamk_f32 v86, v86, 0x3e0293ee, v197
	v_fmamk_f32 v87, v87, 0x3e0293ee, v197
	v_fmamk_f32 v88, v88, 0x3e0293ee, v197
	v_fmamk_f32 v89, v89, 0x3e0293ee, v197
	v_fmamk_f32 v90, v90, 0x3e0293ee, v197
	v_fmamk_f32 v91, v91, 0x3e0293ee, v197
	v_fmamk_f32 v92, v92, 0x3e0293ee, v197
	v_fmamk_f32 v93, v93, 0x3e0293ee, v197
	v_fmamk_f32 v94, v94, 0x3e0293ee, v197
	v_fmamk_f32 v95, v95, 0x3e0293ee, v197
	v_fmamk_f32 v96, v96, 0x3e0293ee, v197
	v_fmamk_f32 v97, v97, 0x3e0293ee, v197
	v_exp_f32_e32 v168, v82
	v_exp_f32_e32 v175, v83
	v_exp_f32_e32 v145, v84
	v_exp_f32_e32 v146, v85
	v_exp_f32_e32 v172, v86
	v_exp_f32_e32 v176, v87
	v_exp_f32_e32 v147, v88
	v_exp_f32_e32 v148, v89
	v_exp_f32_e32 v173, v90
	v_exp_f32_e32 v177, v91
	v_exp_f32_e32 v149, v92
	v_exp_f32_e32 v150, v93
	v_exp_f32_e32 v174, v94
	v_exp_f32_e32 v178, v95
	v_exp_f32_e32 v151, v96
	v_exp_f32_e32 v167, v97
	v_fmamk_f32 v179, v66, 0x3e0293ee, v197
	v_fmamk_f32 v196, v67, 0x3e0293ee, v197
	v_fmamk_f32 v198, v68, 0x3e0293ee, v197
	v_fmamk_f32 v199, v69, 0x3e0293ee, v197
	v_fmamk_f32 v209, v70, 0x3e0293ee, v197
	v_fmamk_f32 v226, v71, 0x3e0293ee, v197
	v_fmamk_f32 v227, v72, 0x3e0293ee, v197
	v_fmamk_f32 v228, v73, 0x3e0293ee, v197
	v_fmamk_f32 v229, v74, 0x3e0293ee, v197
	v_fmamk_f32 v230, v75, 0x3e0293ee, v197
	v_fmamk_f32 v231, v76, 0x3e0293ee, v197
	v_fmamk_f32 v232, v77, 0x3e0293ee, v197
	v_fmamk_f32 v233, v78, 0x3e0293ee, v197
	v_fmamk_f32 v234, v79, 0x3e0293ee, v197
	v_fmamk_f32 v235, v80, 0x3e0293ee, v197
	v_fmac_f32_e32 v197, 0x3e0293ee, v81
	s_waitcnt lgkmcnt(0)
	s_barrier
	v_add3_u32 v66, s55, v159, v154
	v_add3_u32 v67, s55, v160, v154
	ds_read_b128 v[180:183], v66 offset:24576
	ds_read_b128 v[188:191], v66 offset:28672
	ds_read_b128 v[184:187], v67 offset:24576
	ds_read_b128 v[192:195], v67 offset:28672
	v_add3_u32 v66, s55, v161, v154
	v_add3_u32 v67, s55, v162, v154
	ds_read_b128 v[210:213], v66 offset:24576
	ds_read_b128 v[218:221], v66 offset:28672
	ds_read_b128 v[214:217], v67 offset:24576
	ds_read_b128 v[222:225], v67 offset:28672
	s_nop 1
	s_setprio 1
	v_mov_b64_e32 v[80:81], s[50:51]
	v_mov_b64_e32 v[78:79], s[48:49]
	v_mov_b64_e32 v[76:77], s[46:47]
	v_mov_b64_e32 v[74:75], s[44:45]
	v_mov_b64_e32 v[72:73], s[42:43]
	v_mov_b64_e32 v[70:71], s[40:41]
	v_mov_b64_e32 v[68:69], s[38:39]
	v_mov_b64_e32 v[66:67], s[36:37]
	v_mov_b64_e32 v[96:97], v[80:81]
	v_mov_b64_e32 v[94:95], v[78:79]
	v_mov_b64_e32 v[92:93], v[76:77]
	v_mov_b64_e32 v[90:91], v[74:75]
	v_mov_b64_e32 v[88:89], v[72:73]
	v_mov_b64_e32 v[86:87], v[70:71]
	v_mov_b64_e32 v[84:85], v[68:69]
	v_mov_b64_e32 v[82:83], v[66:67]
	s_waitcnt lgkmcnt(0)
	v_mfma_scale_f32_32x32x64_f8f6f4 v[82:97], v[180:187], v[98:105], v[82:97], v133, v133 op_sel_hi:[0,0,0]
	v_mfma_scale_f32_32x32x64_f8f6f4 v[66:81], v[188:195], v[98:105], v[66:81], v133, v133 op_sel_hi:[0,0,0]
	s_nop 0
	v_mfma_scale_f32_32x32x64_f8f6f4 v[82:97], v[210:217], v[106:113], v[82:97], v133, v133 op_sel_hi:[0,0,0]
	v_mfma_scale_f32_32x32x64_f8f6f4 v[66:81], v[218:225], v[106:113], v[66:81], v133, v133 op_sel_hi:[0,0,0]
	s_setprio 0
	v_add_f32_e32 v188, 0, v168
	v_add_f32_e32 v188, v175, v188
	v_add_f32_e32 v188, v145, v188
	v_add_f32_e32 v188, v146, v188
	v_add_f32_e32 v188, v172, v188
	v_add_f32_e32 v188, v176, v188
	v_add_f32_e32 v188, v147, v188
	v_add_f32_e32 v188, v148, v188
	v_add_f32_e32 v188, v173, v188
	v_add_f32_e32 v188, v177, v188
	v_add_f32_e32 v188, v149, v188
	v_add_f32_e32 v188, v150, v188
	v_exp_f32_e32 v187, v179
	v_add_f32_e32 v188, v174, v188
	v_exp_f32_e32 v193, v196
	v_add_f32_e32 v188, v178, v188
	v_exp_f32_e32 v179, v198
	v_add_f32_e32 v188, v151, v188
	v_exp_f32_e32 v180, v199
	v_add_f32_e32 v188, v167, v188
	v_exp_f32_e32 v190, v209
	v_add_f32_e32 v188, v187, v188
	v_exp_f32_e32 v194, v226
	v_add_f32_e32 v188, v193, v188
	v_exp_f32_e32 v181, v227
	v_add_f32_e32 v188, v179, v188
	v_exp_f32_e32 v182, v228
	v_add_f32_e32 v188, v180, v188
	v_exp_f32_e32 v191, v229
	v_add_f32_e32 v188, v190, v188
	v_exp_f32_e32 v195, v230
	v_add_f32_e32 v188, v194, v188
	v_exp_f32_e32 v183, v231
	v_add_f32_e32 v188, v181, v188
	v_exp_f32_e32 v184, v232
	v_add_f32_e32 v188, v182, v188
	v_exp_f32_e32 v192, v233
	v_add_f32_e32 v188, v191, v188
	v_exp_f32_e32 v196, v234
	v_add_f32_e32 v188, v195, v188
	v_exp_f32_e32 v185, v235
	v_add_f32_e32 v188, v183, v188
	v_exp_f32_e32 v186, v197
	v_add_f32_e32 v188, v184, v188
	v_add_f32_e32 v188, v192, v188
	v_add_f32_e32 v188, v196, v188
	v_add_f32_e32 v188, v185, v188
	v_add_f32_e32 v188, v186, v188
	v_mov_b32_e32 v189, v188
	s_nop 1
	v_permlane32_swap_b32_e32 v188, v189
	s_cmp_ge_u32 s84, s83
	s_cselect_b64 s[24:25], -1, 0
	s_and_b64 vcc, exec, s[24:25]
	s_cbranch_vccz .Lattn_doB
	s_waitcnt vmcnt(0)
	s_branch .LBB0_555
; #define SBAR() __builtin_amdgcn_sched_barrier(0)
; #define SLOAD8(i, t) do { sk[i] = *reinterpret_cast<const i32x4a*>(kg + (long)(t) * (64 * 512)); sv[i] = *reinterpret_cast<const i32x4a*>(vg + (long)(t) * VT_STRIDE); } while (0)
; #define SWAIT8() asm volatile("s_waitcnt vmcnt(2)" ::: "memory")
; #define SWRITE8R(boff, i) do { *reinterpret_cast<ATT_LAS i32x4a*>(K_lds + (boff) + kst) = sk[i]; *reinterpret_cast<ATT_LAS i32x4a*>(V_lds + (boff) + vst) = sv[i]; } while (0)
; #define RESC8(a) do { if (__any((a) < 1.f)) { if (hi == 0) al_l[r32] = (a); asm volatile("s_waitcnt lgkmcnt(0)" ::: "memory"); \
;     _Pragma("unroll") for (int d = 0; d < 4; ++d) _Pragma("unroll") for (int r = 0; r < 16; ++r) o[d][r] *= al_l[crow(r, hi)]; } } while (0)
; __device__ __forceinline__ void attn_unit8(const bf16_t* __restrict__ Qb, const unsigned char* __restrict__ K8h, const unsigned char* __restrict__ VT8h, unsigned char* __restrict__ Ob, int seq, ATT_LAS char* lds, ...
;     ...
;     if (j + 3 < NT) SLOAD8(0, j + 3); SBAR();
;     pv8<false>(o, V_lds + bV, pa, r32, hi, one); partialSM8(pA0, pA1, m_reg, mnA, alA);
;     SWAIT8(); SWRITE8R(bW, 1);
;     RESC8(alA); __syncthreads();
.Lattn_doB:
	v_add_co_u32_e32 v114, vcc, 0x1da20000, v142
	s_nop 1
	v_addc_co_u32_e32 v115, vcc, 0, v143, vcc
	v_add_co_u32_e32 v116, vcc, 0x1e620000, v140
	s_nop 1
	v_addc_co_u32_e32 v117, vcc, 0, v141, vcc
	global_load_dwordx4 v[118:121], v[114:115], off
	s_nop 0
	global_load_dwordx4 v[114:117], v[116:117], off
.LBB0_555:
	v_mov_b32_e32 v210, 0
	v_mov_b32_e32 v211, 0
	v_mov_b32_e32 v212, 0
	v_mov_b32_e32 v213, 0
	v_mov_b32_e32 v214, 0
	v_mov_b32_e32 v215, 0
	v_mov_b32_e32 v216, 0
	v_mov_b32_e32 v217, 0
	v_cvt_pk_fp8_f32 v210, v168, v175
	v_cvt_pk_fp8_f32 v211, v172, v176
	v_cvt_pk_fp8_f32 v212, v173, v177
	v_cvt_pk_fp8_f32 v213, v174, v178
	v_cvt_pk_fp8_f32 v214, v187, v193
	v_cvt_pk_fp8_f32 v215, v190, v194
	v_cvt_pk_fp8_f32 v216, v191, v195
	v_cvt_pk_fp8_f32 v217, v192, v196
	v_cvt_pk_fp8_f32 v210, v145, v146 op_sel:[0,0,1]
	v_cvt_pk_fp8_f32 v211, v147, v148 op_sel:[0,0,1]
	v_cvt_pk_fp8_f32 v212, v149, v150 op_sel:[0,0,1]
	v_cvt_pk_fp8_f32 v213, v151, v167 op_sel:[0,0,1]
	v_cvt_pk_fp8_f32 v214, v179, v180 op_sel:[0,0,1]
	v_cvt_pk_fp8_f32 v215, v181, v182 op_sel:[0,0,1]
	v_cvt_pk_fp8_f32 v216, v183, v184 op_sel:[0,0,1]
	v_cvt_pk_fp8_f32 v217, v185, v186 op_sel:[0,0,1]
	v_add3_u32 v140, s26, v164, v163
	v_add3_u32 v141, s26, v165, v163
	ds_read_b128 v[172:175], v140
	ds_read_b128 v[180:183], v140 offset:2048
	ds_read_b128 v[176:179], v141
	ds_read_b128 v[184:187], v141 offset:2048
	ds_read_b128 v[190:193], v140 offset:4096
	ds_read_b128 v[218:221], v140 offset:6144
	ds_read_b128 v[194:197], v141 offset:4096
	ds_read_b128 v[222:225], v141 offset:6144
	s_setprio 1
	s_waitcnt lgkmcnt(0)
	v_mfma_scale_f32_32x32x64_f8f6f4 v[2:17], v[210:217], v[172:179], v[2:17], v133, v133 op_sel_hi:[0,0,0]
	v_mfma_scale_f32_32x32x64_f8f6f4 v[50:65], v[210:217], v[180:187], v[50:65], v133, v133 op_sel_hi:[0,0,0]
	v_mfma_scale_f32_32x32x64_f8f6f4 v[34:49], v[210:217], v[190:197], v[34:49], v133, v133 op_sel_hi:[0,0,0]
	v_mfma_scale_f32_32x32x64_f8f6f4 v[18:33], v[210:217], v[218:225], v[18:33], v133, v133 op_sel_hi:[0,0,0]
	s_setprio 0
	v_max_f32_e32 v140, v83, v83
	v_max_f32_e32 v141, v82, v82
	v_max_f32_e32 v140, v141, v140
	v_max3_f32 v140, v140, v84, v85
	v_max3_f32 v140, v140, v86, v87
	v_max3_f32 v140, v140, v88, v89
	v_max3_f32 v140, v140, v90, v91
	v_max3_f32 v140, v140, v92, v93
	v_max3_f32 v140, v140, v94, v95
	v_max3_f32 v140, v140, v96, v97
	v_max3_f32 v140, v140, v66, v67
	v_max3_f32 v140, v140, v68, v69
	v_max3_f32 v140, v140, v70, v71
	v_max3_f32 v140, v140, v72, v73
	v_max3_f32 v140, v140, v74, v75
	v_max3_f32 v140, v140, v76, v77
	v_max3_f32 v140, v140, v78, v79
	v_max3_f32 v140, v140, v80, v81
	v_mov_b32_e32 v141, v140
	s_nop 1
	v_permlane32_swap_b32_e32 v140, v141
	v_max_f32_e32 v141, v141, v141
	v_max_f32_e32 v140, v140, v140
	v_max_f32_e32 v140, v140, v141
	v_max_f32_e32 v142, v144, v144
	v_sub_f32_e32 v141, v140, v144
	v_max_f32_e32 v140, v142, v140
	v_sub_f32_e32 v142, v144, v140
	v_mul_f32_e32 v142, 0x3e0293ee, v142
	v_exp_f32_e32 v142, v142
	v_cmp_ge_f32_e32 vcc, s69, v141
	s_cmp_eq_u64 vcc, exec
	s_cselect_b64 s[8:9], -1, 0
	s_waitcnt vmcnt(2)
	v_cndmask_b32_e64 v168, v142, 1.0, s[8:9]
	v_add_u32_e32 v141, s54, v157
	ds_write_b128 v141, v[122:125] offset:24576
	v_add_u32_e32 v122, s56, v207
	v_cmp_gt_f32_e32 vcc, 1.0, v168
	ds_write_b128 v122, v[126:129]
	s_cbranch_vccz .LBB0_559
	s_and_saveexec_b64 s[26:27], s[6:7]
	ds_write_b32 v152, v168 offset:49280
	s_or_b64 exec, exec, s[26:27]
	s_waitcnt lgkmcnt(0)
	v_add_u32_e32 v141, v206, v134
	ds_read_b128 v[122:125], v141 offset:49376
	ds_read_b128 v[126:129], v141 offset:49344
	ds_read_b128 v[146:149], v141 offset:49312
	ds_read_b128 v[172:175], v141 offset:49280
	s_waitcnt lgkmcnt(3)
	v_pk_mul_f32 v[14:15], v[14:15], v[122:123]
	s_waitcnt lgkmcnt(2)
	v_pk_mul_f32 v[10:11], v[10:11], v[126:127]
	s_waitcnt lgkmcnt(1)
	v_pk_mul_f32 v[6:7], v[6:7], v[146:147]
	v_pk_mul_f32 v[16:17], v[16:17], v[124:125]
	v_pk_mul_f32 v[12:13], v[12:13], v[128:129]
	v_pk_mul_f32 v[8:9], v[8:9], v[148:149]
	s_waitcnt lgkmcnt(0)
	v_pk_mul_f32 v[4:5], v[4:5], v[174:175]
	v_pk_mul_f32 v[2:3], v[2:3], v[172:173]
	v_pk_mul_f32 v[62:63], v[62:63], v[122:123]
	v_pk_mul_f32 v[58:59], v[58:59], v[126:127]
	v_pk_mul_f32 v[54:55], v[54:55], v[146:147]
	v_pk_mul_f32 v[64:65], v[64:65], v[124:125]
	v_pk_mul_f32 v[60:61], v[60:61], v[128:129]
	v_pk_mul_f32 v[56:57], v[56:57], v[148:149]
	v_pk_mul_f32 v[52:53], v[52:53], v[174:175]
	v_pk_mul_f32 v[50:51], v[50:51], v[172:173]
	v_pk_mul_f32 v[46:47], v[46:47], v[122:123]
	v_pk_mul_f32 v[42:43], v[42:43], v[126:127]
	v_pk_mul_f32 v[38:39], v[38:39], v[146:147]
	v_pk_mul_f32 v[48:49], v[48:49], v[124:125]
	v_pk_mul_f32 v[44:45], v[44:45], v[128:129]
	v_pk_mul_f32 v[40:41], v[40:41], v[148:149]
	v_pk_mul_f32 v[36:37], v[36:37], v[174:175]
	v_pk_mul_f32 v[34:35], v[34:35], v[172:173]
	v_pk_mul_f32 v[30:31], v[30:31], v[122:123]
	v_pk_mul_f32 v[26:27], v[26:27], v[126:127]
	v_pk_mul_f32 v[22:23], v[22:23], v[146:147]
	v_pk_mul_f32 v[32:33], v[32:33], v[124:125]
	v_pk_mul_f32 v[28:29], v[28:29], v[128:129]
	v_pk_mul_f32 v[24:25], v[24:25], v[148:149]
	v_pk_mul_f32 v[20:21], v[20:21], v[174:175]
	v_pk_mul_f32 v[18:19], v[18:19], v[172:173]
